# sc1 write-through stores also for the GLU GEMM phase (epilogue and deferred weight conversion)
# baseline (speedup 1.0000x reference)
; #define PG8_STAGE(bufoff, gbase, voff) do { _Pragma("unroll") for (int _i = 0; _i < 2; ++_i) \
;         __builtin_amdgcn_global_load_lds((const unsigned*)((const char*)(gbase) + (voff)[_i]), (LAS unsigned*)(lds + (bufoff) + ldsw + _i * 8192), 16, 0, 0); } while (0)
; #define PG8_LDA(dst, b, h) do { _Pragma("unroll") for (int m = 0; m < 4; ++m) _Pragma("unroll") for (int k = 0; k < 2; ++k) dst[m][k] = *(const LAS bf16x8*)(lds + PG8_SA(b, h) + aoff + m * 2048 + k * 1024); } while (0)
; #define PG8_LDB(dst, b, h) do { _Pragma("unroll") for (int n = 0; n < 2; ++n) _Pragma("unroll") for (int k = 0; k < 2; ++k) dst[n][k] = *(const LAS bf16x8*)(lds + PG8_SB(b, h) + boff + n * 2048 + k * 1024); } while (0)
; #define PG8_MMA(ai, bj, At, Bt) do { __builtin_amdgcn_s_setprio(1); _Pragma("unroll") for (int m = 0; m < 4; ++m) _Pragma("unroll") for (int n = 0; n < 2; ++n) _Pragma("unroll") for (int k = 0; k < 2; ++k) \
;         acc[ai][bj][m][n] = __builtin_amdgcn_mfma_f32_16x16x32_bf16(Bt[n][k], At[m][k], acc[ai][bj][m][n], 0, 0, 0); __builtin_amdgcn_s_setprio(0); } while (0)
; #define PG8_WAIT_L(n) asm volatile("s_waitcnt lgkmcnt(" #n ")" ::: "memory")
; #define PG8_BAR __builtin_amdgcn_s_barrier()
; #define PG8_SCHED __builtin_amdgcn_sched_barrier(0)
; template <class Epi>
; __device__ __forceinline__ void gemm_phase(LAS unsigned char* lds, const Gemm g, const StaticOrder& S, const Epi& E) {
;     ...
;             PG8_LDB(B0, 0, 0); PG8_SCHED; PG8_LDA(At, 0, 0); PG8_STAGE(PG8_SA(1, 1), a1 + hstep, voffA);
;             PG8_WAIT_L(8); PG8_BAR; PG8_WAIT_L(0); PG8_MMA(0, 0, At, B0); PG8_BAR; PG8_SCHED;
;             PG8_LDB(B1, 0, 1); PG8_STAGE(PG8_SB(0, 0), b2, voffB);
;             PG8_BAR; PG8_WAIT_L(0); PG8_MMA(0, 1, At, B1); PG8_BAR;
;             PG8_LDA(At, 0, 1); PG8_STAGE(PG8_SA(0, 0), a2, voffA);
;             PG8_BAR; PG8_WAIT_L(0); PG8_MMA(1, 0, At, B0); PG8_BAR; PG8_SCHED;
.LBB0_739:
	ds_read_b128 v[64:67], v198
	ds_read_b128 v[68:71], v198 offset:1024
	ds_read_b128 v[80:83], v198 offset:2048
	ds_read_b128 v[84:87], v198 offset:3072
	s_add_u32 s40, s34, 0xfffc0080
	s_addc_u32 s41, s35, -1
	s_cmp_eq_u32 s63, 12
	s_cselect_b32 s43, s25, s41
	s_cselect_b32 s42, s59, s40
	s_cselect_b32 s41, s23, s62
	s_cselect_b32 s40, s60, s61
	v_lshl_add_u64 v[202:203], s[34:35], 0, v[172:173]
	s_add_i32 m0, s31, 0xc000
	ds_read_b128 v[144:147], v199
	ds_read_b128 v[148:151], v199 offset:1024
	ds_read_b128 v[152:155], v199 offset:2048
	ds_read_b128 v[156:159], v199 offset:3072
	ds_read_b128 v[160:163], v199 offset:4096
	ds_read_b128 v[180:183], v199 offset:5120
	ds_read_b128 v[184:187], v199 offset:6144
	ds_read_b128 v[188:191], v199 offset:7168
	global_load_lds_dwordx4 v[202:203], off
	v_lshl_add_u64 v[202:203], s[34:35], 0, v[174:175]
	s_add_i32 m0, s31, 0xe000
	s_nop 0
	global_load_lds_dwordx4 v[202:203], off
	s_waitcnt lgkmcnt(8)
	s_barrier
	s_waitcnt lgkmcnt(0)
	s_waitcnt lgkmcnt(0)
	v_mfma_f32_16x16x32_bf16 v[140:143], v[64:67], v[144:147], v[140:143]
	v_mfma_f32_16x16x32_bf16 v[136:139], v[80:83], v[144:147], v[136:139]
	v_mfma_f32_16x16x32_bf16 v[124:127], v[64:67], v[152:155], v[124:127]
	v_mfma_f32_16x16x32_bf16 v[120:123], v[80:83], v[152:155], v[120:123]
	v_mfma_f32_16x16x32_bf16 v[108:111], v[64:67], v[160:163], v[108:111]
	v_mfma_f32_16x16x32_bf16 v[104:107], v[80:83], v[160:163], v[104:107]
	v_mfma_f32_16x16x32_bf16 v[92:95], v[64:67], v[184:187], v[92:95]
	v_mfma_f32_16x16x32_bf16 v[88:91], v[80:83], v[184:187], v[88:91]
	v_mfma_f32_16x16x32_bf16 v[140:143], v[68:71], v[148:151], v[140:143]
	v_mfma_f32_16x16x32_bf16 v[136:139], v[84:87], v[148:151], v[136:139]
	v_mfma_f32_16x16x32_bf16 v[124:127], v[68:71], v[156:159], v[124:127]
	v_mfma_f32_16x16x32_bf16 v[120:123], v[84:87], v[156:159], v[120:123]
	v_mfma_f32_16x16x32_bf16 v[108:111], v[68:71], v[180:183], v[108:111]
	v_mfma_f32_16x16x32_bf16 v[104:107], v[84:87], v[180:183], v[104:107]
	v_mfma_f32_16x16x32_bf16 v[92:95], v[68:71], v[188:191], v[92:95]
	v_mfma_f32_16x16x32_bf16 v[88:91], v[84:87], v[188:191], v[88:91]
	s_barrier
	s_add_i32 s64, s56, s44
	v_lshl_add_u64 v[220:221], s[40:41], 0, v[166:167]
	s_mov_b32 m0, s64
	ds_read_b128 v[202:205], v200
	ds_read_b128 v[206:209], v200 offset:1024
	ds_read_b128 v[210:213], v200 offset:2048
	ds_read_b128 v[216:219], v200 offset:3072
	global_load_lds_dwordx4 v[220:221], off
	v_lshl_add_u64 v[222:223], s[40:41], 0, v[170:171]
	s_add_i32 m0, s64, 0x2000
	s_nop 0
	global_load_lds_dwordx4 v[222:223], off
	s_barrier
	s_waitcnt lgkmcnt(0)
	s_waitcnt lgkmcnt(0)
	v_mfma_f32_16x16x32_bf16 v[132:135], v[202:205], v[144:147], v[132:135]
	v_mfma_f32_16x16x32_bf16 v[128:131], v[210:213], v[144:147], v[128:131]
	v_mfma_f32_16x16x32_bf16 v[116:119], v[202:205], v[152:155], v[116:119]
	v_mfma_f32_16x16x32_bf16 v[112:115], v[210:213], v[152:155], v[112:115]
	v_mfma_f32_16x16x32_bf16 v[100:103], v[202:205], v[160:163], v[100:103]
	v_mfma_f32_16x16x32_bf16 v[96:99], v[210:213], v[160:163], v[96:99]
	v_mfma_f32_16x16x32_bf16 v[76:79], v[202:205], v[184:187], v[76:79]
	v_mfma_f32_16x16x32_bf16 v[72:75], v[210:213], v[184:187], v[72:75]
	v_mfma_f32_16x16x32_bf16 v[132:135], v[206:209], v[148:151], v[132:135]
	v_mfma_f32_16x16x32_bf16 v[128:131], v[216:219], v[148:151], v[128:131]
	v_mfma_f32_16x16x32_bf16 v[116:119], v[206:209], v[156:159], v[116:119]
	v_mfma_f32_16x16x32_bf16 v[112:115], v[216:219], v[156:159], v[112:115]
	v_mfma_f32_16x16x32_bf16 v[100:103], v[206:209], v[180:183], v[100:103]
	v_mfma_f32_16x16x32_bf16 v[96:99], v[216:219], v[180:183], v[96:99]
	v_mfma_f32_16x16x32_bf16 v[76:79], v[206:209], v[188:191], v[76:79]
	v_mfma_f32_16x16x32_bf16 v[72:75], v[216:219], v[188:191], v[72:75]
	s_mov_b32 m0, s31
	v_lshl_add_u64 v[224:225], s[42:43], 0, v[164:165]
	s_barrier
	ds_read_b128 v[144:147], v199 offset:16384
	ds_read_b128 v[148:151], v199 offset:17408
	ds_read_b128 v[152:155], v199 offset:18432
	ds_read_b128 v[156:159], v199 offset:19456
	ds_read_b128 v[160:163], v199 offset:20480
	ds_read_b128 v[180:183], v199 offset:21504
	ds_read_b128 v[184:187], v199 offset:22528
	ds_read_b128 v[188:191], v199 offset:23552
	global_load_lds_dwordx4 v[224:225], off
	v_lshl_add_u64 v[226:227], s[42:43], 0, v[168:169]
	s_mov_b32 m0, s45
	s_nop 0
	global_load_lds_dwordx4 v[226:227], off
	s_barrier
	s_waitcnt lgkmcnt(0)
	s_waitcnt lgkmcnt(0)
	v_mfma_f32_16x16x32_bf16 v[60:63], v[64:67], v[144:147], v[60:63]
	v_mfma_f32_16x16x32_bf16 v[56:59], v[80:83], v[144:147], v[56:59]
	v_mfma_f32_16x16x32_bf16 v[44:47], v[64:67], v[152:155], v[44:47]
	v_mfma_f32_16x16x32_bf16 v[40:43], v[80:83], v[152:155], v[40:43]
	v_mfma_f32_16x16x32_bf16 v[28:31], v[64:67], v[160:163], v[28:31]
	v_mfma_f32_16x16x32_bf16 v[24:27], v[80:83], v[160:163], v[24:27]
	v_mfma_f32_16x16x32_bf16 v[12:15], v[64:67], v[184:187], v[12:15]
	v_mfma_f32_16x16x32_bf16 v[8:11], v[80:83], v[184:187], v[8:11]
	v_mfma_f32_16x16x32_bf16 v[60:63], v[68:71], v[148:151], v[60:63]
	v_mfma_f32_16x16x32_bf16 v[56:59], v[84:87], v[148:151], v[56:59]
	v_mfma_f32_16x16x32_bf16 v[44:47], v[68:71], v[156:159], v[44:47]
	v_mfma_f32_16x16x32_bf16 v[40:43], v[84:87], v[156:159], v[40:43]
	v_mfma_f32_16x16x32_bf16 v[28:31], v[68:71], v[180:183], v[28:31]
	v_mfma_f32_16x16x32_bf16 v[24:27], v[84:87], v[180:183], v[24:27]
	v_mfma_f32_16x16x32_bf16 v[12:15], v[68:71], v[188:191], v[12:15]
	v_mfma_f32_16x16x32_bf16 v[8:11], v[84:87], v[188:191], v[8:11]
	s_barrier
; #define PG8_STAGE(bufoff, gbase, voff) do { _Pragma("unroll") for (int _i = 0; _i < 2; ++_i) \
;         __builtin_amdgcn_global_load_lds((const unsigned*)((const char*)(gbase) + (voff)[_i]), (LAS unsigned*)(lds + (bufoff) + ldsw + _i * 8192), 16, 0, 0); } while (0)
; #define PG8_LDA(dst, b, h) do { _Pragma("unroll") for (int m = 0; m < 4; ++m) _Pragma("unroll") for (int k = 0; k < 2; ++k) dst[m][k] = *(const LAS bf16x8*)(lds + PG8_SA(b, h) + aoff + m * 2048 + k * 1024); } while (0)
; #define PG8_LDB(dst, b, h) do { _Pragma("unroll") for (int n = 0; n < 2; ++n) _Pragma("unroll") for (int k = 0; k < 2; ++k) dst[n][k] = *(const LAS bf16x8*)(lds + PG8_SB(b, h) + boff + n * 2048 + k * 1024); } while (0)
; #define PG8_MMA(ai, bj, At, Bt) do { __builtin_amdgcn_s_setprio(1); _Pragma("unroll") for (int m = 0; m < 4; ++m) _Pragma("unroll") for (int n = 0; n < 2; ++n) _Pragma("unroll") for (int k = 0; k < 2; ++k) \
;         acc[ai][bj][m][n] = __builtin_amdgcn_mfma_f32_16x16x32_bf16(Bt[n][k], At[m][k], acc[ai][bj][m][n], 0, 0, 0); __builtin_amdgcn_s_setprio(0); } while (0)
; #define PG8_WAIT_V(n) asm volatile("s_waitcnt vmcnt(" #n ")" ::: "memory")
; #define PG8_WAIT_L(n) asm volatile("s_waitcnt lgkmcnt(" #n ")" ::: "memory")
; #define PG8_BAR __builtin_amdgcn_s_barrier()
; #define PG8_SCHED __builtin_amdgcn_sched_barrier(0)
; template <class Epi>
; __device__ __forceinline__ void gemm_phase(LAS unsigned char* lds, const Gemm g, const StaticOrder& S, const Epi& E) {
;     ...
;             PG8_BAR; PG8_WAIT_L(0); PG8_MMA(1, 0, At, B0); PG8_BAR; PG8_SCHED;
;             PG8_STAGE(PG8_SB(0, 1), b2 + hstep, voffB);
;             PG8_WAIT_V(6); PG8_BAR; PG8_MMA(1, 1, At, B1); PG8_BAR;
;             PG8_LDB(B0, 1, 0); PG8_SCHED; PG8_LDA(At, 1, 0); PG8_STAGE(PG8_SA(0, 1), a2 + hstep, voffA);
;             PG8_WAIT_L(8); PG8_BAR; PG8_WAIT_L(0); PG8_MMA(0, 0, At, B0); PG8_BAR; PG8_SCHED;
;             PG8_LDB(B1, 1, 1); PG8_STAGE(PG8_SB(1, 0), b3, voffB);
;             PG8_BAR; PG8_WAIT_L(0); PG8_MMA(0, 1, At, B1); PG8_BAR;
;             PG8_LDA(At, 1, 1); PG8_STAGE(PG8_SA(1, 0), a3, voffA);
	s_add_u32 s64, s40, 0x40000
	s_addc_u32 s65, s41, 0
	s_add_i32 s66, s57, s44
	v_lshl_add_u64 v[64:65], s[64:65], 0, v[166:167]
	s_mov_b32 m0, s66
	s_nop 0
	global_load_lds_dwordx4 v[64:65], off
	v_lshl_add_u64 v[64:65], s[64:65], 0, v[170:171]
	s_add_i32 m0, s66, 0x2000
	s_nop 0
	global_load_lds_dwordx4 v[64:65], off
	s_waitcnt vmcnt(6)
	s_barrier
	v_mfma_f32_16x16x32_bf16 v[52:55], v[202:205], v[144:147], v[52:55]
	v_mfma_f32_16x16x32_bf16 v[48:51], v[210:213], v[144:147], v[48:51]
	v_mfma_f32_16x16x32_bf16 v[36:39], v[202:205], v[152:155], v[36:39]
	v_mfma_f32_16x16x32_bf16 v[32:35], v[210:213], v[152:155], v[32:35]
	v_mfma_f32_16x16x32_bf16 v[20:23], v[202:205], v[160:163], v[20:23]
	v_mfma_f32_16x16x32_bf16 v[16:19], v[210:213], v[160:163], v[16:19]
	v_mfma_f32_16x16x32_bf16 v[4:7], v[202:205], v[184:187], v[4:7]
	v_mfma_f32_16x16x32_bf16 v[0:3], v[210:213], v[184:187], v[0:3]
	v_mfma_f32_16x16x32_bf16 v[52:55], v[206:209], v[148:151], v[52:55]
	v_mfma_f32_16x16x32_bf16 v[48:51], v[216:219], v[148:151], v[48:51]
	v_mfma_f32_16x16x32_bf16 v[36:39], v[206:209], v[156:159], v[36:39]
	v_mfma_f32_16x16x32_bf16 v[32:35], v[216:219], v[156:159], v[32:35]
	v_mfma_f32_16x16x32_bf16 v[20:23], v[206:209], v[180:183], v[20:23]
	v_mfma_f32_16x16x32_bf16 v[16:19], v[216:219], v[180:183], v[16:19]
	v_mfma_f32_16x16x32_bf16 v[4:7], v[206:209], v[188:191], v[4:7]
	v_mfma_f32_16x16x32_bf16 v[0:3], v[216:219], v[188:191], v[0:3]
	s_add_i32 s64, 0, 0x18000
	v_add_u32_e32 v84, s64, v196
	s_barrier
	ds_read_b128 v[64:67], v84
	ds_read_b128 v[68:71], v84 offset:1024
	ds_read_b128 v[80:83], v84 offset:2048
	ds_read_b128 v[84:87], v84 offset:3072
	s_add_u32 s42, s42, 0x40000
	s_addc_u32 s43, s43, 0
	s_mov_b32 m0, s46
	v_lshl_add_u64 v[202:203], s[42:43], 0, v[164:165]
	ds_read_b128 v[144:147], v199 offset:32768
	ds_read_b128 v[148:151], v199 offset:33792
	ds_read_b128 v[152:155], v199 offset:34816
	ds_read_b128 v[156:159], v199 offset:35840
	ds_read_b128 v[160:163], v199 offset:36864
	ds_read_b128 v[180:183], v199 offset:37888
	ds_read_b128 v[184:187], v199 offset:38912
	ds_read_b128 v[188:191], v199 offset:39936
	global_load_lds_dwordx4 v[202:203], off
	v_lshl_add_u64 v[202:203], s[42:43], 0, v[168:169]
	s_mov_b32 m0, s47
	s_nop 0
	global_load_lds_dwordx4 v[202:203], off
	s_waitcnt lgkmcnt(8)
	s_barrier
	s_waitcnt lgkmcnt(0)
	s_waitcnt lgkmcnt(0)
	v_mfma_f32_16x16x32_bf16 v[140:143], v[64:67], v[144:147], v[140:143]
	v_mfma_f32_16x16x32_bf16 v[136:139], v[80:83], v[144:147], v[136:139]
	v_mfma_f32_16x16x32_bf16 v[124:127], v[64:67], v[152:155], v[124:127]
	v_mfma_f32_16x16x32_bf16 v[120:123], v[80:83], v[152:155], v[120:123]
	v_mfma_f32_16x16x32_bf16 v[108:111], v[64:67], v[160:163], v[108:111]
	v_mfma_f32_16x16x32_bf16 v[104:107], v[80:83], v[160:163], v[104:107]
	v_mfma_f32_16x16x32_bf16 v[92:95], v[64:67], v[184:187], v[92:95]
	v_mfma_f32_16x16x32_bf16 v[88:91], v[80:83], v[184:187], v[88:91]
	v_mfma_f32_16x16x32_bf16 v[140:143], v[68:71], v[148:151], v[140:143]
	v_mfma_f32_16x16x32_bf16 v[136:139], v[84:87], v[148:151], v[136:139]
	v_mfma_f32_16x16x32_bf16 v[124:127], v[68:71], v[156:159], v[124:127]
	v_mfma_f32_16x16x32_bf16 v[120:123], v[84:87], v[156:159], v[120:123]
	v_mfma_f32_16x16x32_bf16 v[108:111], v[68:71], v[180:183], v[108:111]
	v_mfma_f32_16x16x32_bf16 v[104:107], v[84:87], v[180:183], v[104:107]
	v_mfma_f32_16x16x32_bf16 v[92:95], v[68:71], v[188:191], v[92:95]
	v_mfma_f32_16x16x32_bf16 v[88:91], v[84:87], v[188:191], v[88:91]
	s_barrier
	s_add_i32 s42, 0, 0x1c000
	s_add_i32 s43, s64, s44
	v_add_u32_e32 v201, s42, v196
	v_lshl_add_u64 v[220:221], v[220:221], 0, s[10:11]
	s_mov_b32 m0, s43
	ds_read_b128 v[202:205], v201
	ds_read_b128 v[206:209], v201 offset:1024
	ds_read_b128 v[210:213], v201 offset:2048
	ds_read_b128 v[216:219], v201 offset:3072
	global_load_lds_dwordx4 v[220:221], off
	v_lshl_add_u64 v[220:221], v[222:223], 0, s[10:11]
	s_add_i32 m0, s43, 0x2000
	s_nop 0
	global_load_lds_dwordx4 v[220:221], off
	s_barrier
	s_waitcnt lgkmcnt(0)
	s_waitcnt lgkmcnt(0)
	v_mfma_f32_16x16x32_bf16 v[132:135], v[202:205], v[144:147], v[132:135]
	v_mfma_f32_16x16x32_bf16 v[128:131], v[210:213], v[144:147], v[128:131]
	v_mfma_f32_16x16x32_bf16 v[116:119], v[202:205], v[152:155], v[116:119]
	v_mfma_f32_16x16x32_bf16 v[112:115], v[210:213], v[152:155], v[112:115]
	v_mfma_f32_16x16x32_bf16 v[100:103], v[202:205], v[160:163], v[100:103]
	v_mfma_f32_16x16x32_bf16 v[96:99], v[210:213], v[160:163], v[96:99]
	v_mfma_f32_16x16x32_bf16 v[76:79], v[202:205], v[184:187], v[76:79]
	v_mfma_f32_16x16x32_bf16 v[72:75], v[210:213], v[184:187], v[72:75]
	v_mfma_f32_16x16x32_bf16 v[132:135], v[206:209], v[148:151], v[132:135]
	v_mfma_f32_16x16x32_bf16 v[128:131], v[216:219], v[148:151], v[128:131]
	v_mfma_f32_16x16x32_bf16 v[116:119], v[206:209], v[156:159], v[116:119]
	v_mfma_f32_16x16x32_bf16 v[112:115], v[216:219], v[156:159], v[112:115]
	v_mfma_f32_16x16x32_bf16 v[100:103], v[206:209], v[180:183], v[100:103]
	v_mfma_f32_16x16x32_bf16 v[96:99], v[216:219], v[180:183], v[96:99]
	v_mfma_f32_16x16x32_bf16 v[76:79], v[206:209], v[188:191], v[76:79]
	v_mfma_f32_16x16x32_bf16 v[72:75], v[216:219], v[188:191], v[72:75]
	s_mov_b32 m0, s51
	v_lshl_add_u64 v[220:221], v[224:225], 0, s[10:11]
	s_barrier
	ds_read_b128 v[144:147], v199 offset:49152
	ds_read_b128 v[148:151], v199 offset:50176
	ds_read_b128 v[152:155], v199 offset:51200
	ds_read_b128 v[156:159], v199 offset:52224
	ds_read_b128 v[160:163], v199 offset:53248
	ds_read_b128 v[180:183], v199 offset:54272
	ds_read_b128 v[184:187], v199 offset:55296
	ds_read_b128 v[188:191], v199 offset:56320
	global_load_lds_dwordx4 v[220:221], off
	v_lshl_add_u64 v[220:221], v[226:227], 0, s[10:11]
	s_mov_b32 m0, s54
	s_nop 0
	global_load_lds_dwordx4 v[220:221], off
	s_barrier
; #define PG8_STAGE(bufoff, gbase, voff) do { _Pragma("unroll") for (int _i = 0; _i < 2; ++_i) \
;         __builtin_amdgcn_global_load_lds((const unsigned*)((const char*)(gbase) + (voff)[_i]), (LAS unsigned*)(lds + (bufoff) + ldsw + _i * 8192), 16, 0, 0); } while (0)
; #define PG8_LDA(dst, b, h) do { _Pragma("unroll") for (int m = 0; m < 4; ++m) _Pragma("unroll") for (int k = 0; k < 2; ++k) dst[m][k] = *(const LAS bf16x8*)(lds + PG8_SA(b, h) + aoff + m * 2048 + k * 1024); } while (0)
; #define PG8_MMA(ai, bj, At, Bt) do { __builtin_amdgcn_s_setprio(1); _Pragma("unroll") for (int m = 0; m < 4; ++m) _Pragma("unroll") for (int n = 0; n < 2; ++n) _Pragma("unroll") for (int k = 0; k < 2; ++k) \
;         acc[ai][bj][m][n] = __builtin_amdgcn_mfma_f32_16x16x32_bf16(Bt[n][k], At[m][k], acc[ai][bj][m][n], 0, 0, 0); __builtin_amdgcn_s_setprio(0); } while (0)
; #define PG8_WAIT_V(n) asm volatile("s_waitcnt vmcnt(" #n ")" ::: "memory")
; #define PG8_WAIT_L(n) asm volatile("s_waitcnt lgkmcnt(" #n ")" ::: "memory")
; #define PG8_BAR __builtin_amdgcn_s_barrier()
; #define PG8_SCHED __builtin_amdgcn_sched_barrier(0)
; template <class Epi>
; __device__ __forceinline__ void gemm_phase(LAS unsigned char* lds, const Gemm g, const StaticOrder& S, const Epi& E) {
;     ...
;             PG8_LDA(At, 1, 1); PG8_STAGE(PG8_SA(1, 0), a3, voffA);
;             PG8_BAR; PG8_WAIT_L(0); PG8_MMA(1, 0, At, B0); PG8_BAR; PG8_SCHED;
;             PG8_STAGE(PG8_SB(1, 1), b3 + hstep, voffB);
;             PG8_WAIT_V(6); PG8_BAR; PG8_MMA(1, 1, At, B1); PG8_BAR;
;         }
;     __device__ __forceinline__ void operator()(const AccT& acc, const pg8::Unit& u, int wr, int wc, int fr, int fq) const {
;         const int row0 = u.pm * 256 + wr * 64 + fr, col0 = u.pn * 256 + wc * 32 + 8 * fq;
;         f32x4 bv[2][2];
; #pragma unroll
;         for (int bj = 0; bj < 2; ++bj)
; #pragma unroll
;             for (int n = 0; n < 2; ++n) bv[bj][n] = *(const f32x4*)(bias + col0 + bj * 128 + 4 * n);
; #pragma unroll
;         for (int ai = 0; ai < 2; ++ai) { u32x4 gw[4][2];
; #pragma unroll
;             for (int m = 0; m < 4; ++m)
; #pragma unroll
;                 for (int bj = 0; bj < 2; ++bj) gw[m][bj] = *(const u32x4*)(G + (size_t)(row0 + ai * 128 + m * 16) * 1024 + col0 + bj * 128);
	s_waitcnt lgkmcnt(0)
	s_waitcnt lgkmcnt(0)
	v_mfma_f32_16x16x32_bf16 v[60:63], v[64:67], v[144:147], v[60:63]
	v_mfma_f32_16x16x32_bf16 v[56:59], v[80:83], v[144:147], v[56:59]
	v_mfma_f32_16x16x32_bf16 v[44:47], v[64:67], v[152:155], v[44:47]
	v_mfma_f32_16x16x32_bf16 v[40:43], v[80:83], v[152:155], v[40:43]
	v_mfma_f32_16x16x32_bf16 v[28:31], v[64:67], v[160:163], v[28:31]
	v_mfma_f32_16x16x32_bf16 v[24:27], v[80:83], v[160:163], v[24:27]
	v_mfma_f32_16x16x32_bf16 v[12:15], v[64:67], v[184:187], v[12:15]
	v_mfma_f32_16x16x32_bf16 v[8:11], v[80:83], v[184:187], v[8:11]
	v_mfma_f32_16x16x32_bf16 v[60:63], v[68:71], v[148:151], v[60:63]
	v_mfma_f32_16x16x32_bf16 v[56:59], v[84:87], v[148:151], v[56:59]
	v_mfma_f32_16x16x32_bf16 v[44:47], v[68:71], v[156:159], v[44:47]
	v_mfma_f32_16x16x32_bf16 v[40:43], v[84:87], v[156:159], v[40:43]
	v_mfma_f32_16x16x32_bf16 v[28:31], v[68:71], v[180:183], v[28:31]
	v_mfma_f32_16x16x32_bf16 v[24:27], v[84:87], v[180:183], v[24:27]
	v_mfma_f32_16x16x32_bf16 v[12:15], v[68:71], v[188:191], v[12:15]
	v_mfma_f32_16x16x32_bf16 v[8:11], v[84:87], v[188:191], v[8:11]
	s_barrier
	s_add_u32 s40, s40, 0x40080
	s_addc_u32 s41, s41, 0
	s_add_i32 s42, s42, s44
	v_lshl_add_u64 v[64:65], s[40:41], 0, v[166:167]
	s_mov_b32 m0, s42
	s_nop 0
	global_load_lds_dwordx4 v[64:65], off
	v_lshl_add_u64 v[64:65], s[40:41], 0, v[170:171]
	s_add_i32 m0, s42, 0x2000
	s_nop 0
	global_load_lds_dwordx4 v[64:65], off
	s_waitcnt vmcnt(6)
	s_barrier
	v_mfma_f32_16x16x32_bf16 v[52:55], v[202:205], v[144:147], v[52:55]
	v_mfma_f32_16x16x32_bf16 v[48:51], v[210:213], v[144:147], v[48:51]
	v_mfma_f32_16x16x32_bf16 v[36:39], v[202:205], v[152:155], v[36:39]
	v_mfma_f32_16x16x32_bf16 v[32:35], v[210:213], v[152:155], v[32:35]
	v_mfma_f32_16x16x32_bf16 v[20:23], v[202:205], v[160:163], v[20:23]
	v_mfma_f32_16x16x32_bf16 v[16:19], v[210:213], v[160:163], v[16:19]
	v_mfma_f32_16x16x32_bf16 v[4:7], v[202:205], v[184:187], v[4:7]
	v_mfma_f32_16x16x32_bf16 v[0:3], v[210:213], v[184:187], v[0:3]
	v_mfma_f32_16x16x32_bf16 v[52:55], v[206:209], v[148:151], v[52:55]
	v_mfma_f32_16x16x32_bf16 v[48:51], v[216:219], v[148:151], v[48:51]
	v_mfma_f32_16x16x32_bf16 v[36:39], v[206:209], v[156:159], v[36:39]
	v_mfma_f32_16x16x32_bf16 v[32:35], v[216:219], v[156:159], v[32:35]
	v_mfma_f32_16x16x32_bf16 v[20:23], v[206:209], v[180:183], v[20:23]
	v_mfma_f32_16x16x32_bf16 v[16:19], v[216:219], v[180:183], v[16:19]
	v_mfma_f32_16x16x32_bf16 v[4:7], v[206:209], v[188:191], v[4:7]
	v_mfma_f32_16x16x32_bf16 v[0:3], v[216:219], v[188:191], v[0:3]
	s_add_i32 s63, s63, 2
	s_add_u32 s34, s34, 0x100
	s_addc_u32 s35, s35, 0
	s_add_u32 s61, s61, 0x100
	s_addc_u32 s62, s62, 0
	s_cmp_gt_u32 s63, 13
	s_barrier
	s_cbranch_scc0 .LBB0_739
	v_lshl_or_b32 v64, s58, 8, v197
	v_ashrrev_i32_e32 v65, 31, v64
	v_readlane_b32 s60, v245, 18
	v_lshl_add_u32 v144, s30, 8, v195
	v_readlane_b32 s66, v245, 24
	v_readlane_b32 s67, v245, 25
	v_ashrrev_i32_e32 v145, 31, v144
	v_lshlrev_b64 v[180:181], 1, v[64:65]
	v_lshl_add_u64 v[66:67], v[64:65], 2, s[66:67]
	v_lshlrev_b64 v[184:185], 11, v[144:145]
	v_lshl_add_u64 v[182:183], s[6:7], 0, v[180:181]
	global_load_dwordx4 v[84:87], v[66:67], off
	global_load_dwordx4 v[80:83], v[66:67], off offset:16
	global_load_dwordx4 v[68:71], v[66:67], off offset:512
	v_lshl_add_u64 v[64:65], v[182:183], 0, v[184:185]
	global_load_dwordx4 v[202:205], v[64:65], off
	global_load_dwordx4 v[206:209], v[64:65], off offset:256
	s_nop 0
	global_load_dwordx4 v[64:67], v[66:67], off offset:528
	v_or_b32_e32 v146, 16, v144
	v_or_b32_e32 v148, 32, v144
	v_or_b32_e32 v144, 48, v144
	v_ashrrev_i32_e32 v147, 31, v146
	v_ashrrev_i32_e32 v149, 31, v148
	v_ashrrev_i32_e32 v145, 31, v144
	v_lshlrev_b64 v[190:191], 11, v[146:147]
	v_lshlrev_b64 v[188:189], 11, v[148:149]
	v_lshlrev_b64 v[186:187], 11, v[144:145]
	v_lshl_add_u64 v[144:145], s[4:5], 0, v[184:185]
	v_lshl_add_u64 v[146:147], v[182:183], 0, v[190:191]
	v_lshl_add_u64 v[148:149], v[182:183], 0, v[188:189]
	v_lshl_add_u64 v[216:217], v[182:183], 0, v[186:187]
	v_lshl_add_u64 v[218:219], v[144:145], 0, v[180:181]
	global_load_dwordx4 v[210:213], v[146:147], off
	global_load_dwordx4 v[160:163], v[146:147], off offset:256
	global_load_dwordx4 v[156:159], v[148:149], off
	global_load_dwordx4 v[152:155], v[148:149], off offset:256
	s_nop 0
	global_load_dwordx4 v[148:151], v[216:217], off
	global_load_dwordx4 v[144:147], v[216:217], off offset:256
	s_and_b64 vcc, exec, s[2:3]
	s_mov_b32 s58, s22
	s_mov_b32 s30, s24
	s_mov_b64 s[40:41], s[28:29]
	s_mov_b64 s[34:35], s[26:27]
	v_readlane_b32 s61, v245, 19
	v_readlane_b32 s62, v245, 20
	v_readlane_b32 s63, v245, 21
	v_readlane_b32 s64, v245, 22
	v_readlane_b32 s65, v245, 23
	v_readlane_b32 s68, v245, 26
	v_readlane_b32 s69, v245, 27
	v_readlane_b32 s70, v245, 28
	v_readlane_b32 s71, v245, 29
	v_readlane_b32 s72, v245, 30
	v_readlane_b32 s73, v245, 31
	v_readlane_b32 s74, v245, 32
	v_readlane_b32 s75, v245, 33
	s_waitcnt vmcnt(0)
; __device__ __forceinline__ u32x4 pack8(const f32x4 v0, const f32x4 v1) { u32x4 w; w.x = cvt_pk_bf16(v0[0], v0[1]); w.y = cvt_pk_bf16(v0[2], v0[3]); w.z = cvt_pk_bf16(v1[0], v1[1]); w.w = cvt_pk_bf16(v1[2], v1[3]); return w; }
; __device__ __forceinline__ void unpack8(const u32x4 w, f32x4& v0, f32x4& v1) { v0 = (f32x4){bflo(w.x), bfhi(w.x), bflo(w.y), bfhi(w.y)}; v1 = (f32x4){bflo(w.z), bfhi(w.z), bflo(w.w), bfhi(w.w)}; }
; __device__ __forceinline__ f32x4 sig4(const f32x4 v) { return (f32x4){sigmoidf_(v[0]), sigmoidf_(v[1]), sigmoidf_(v[2]), sigmoidf_(v[3])}; }
;     __device__ __forceinline__ void operator()(const AccT& acc, const pg8::Unit& u, int wr, int wc, int fr, int fq) const {
;     ...
;         for (int ai = 0; ai < 2; ++ai) { u32x4 gw[4][2];
; #pragma unroll
;             for (int m = 0; m < 4; ++m)
; #pragma unroll
;                 for (int bj = 0; bj < 2; ++bj) gw[m][bj] = *(const u32x4*)(G + (size_t)(row0 + ai * 128 + m * 16) * 1024 + col0 + bj * 128);
; #pragma unroll
;             for (int m = 0; m < 4; ++m)
; #pragma unroll
;                 for (int bj = 0; bj < 2; ++bj) { f32x4 g0, g1; unpack8(gw[m][bj], g0, g1);
;                     *(u32x4*)(O + (size_t)(row0 + ai * 128 + m * 16) * 1024 + col0 + bj * 128) = pack8(g0 * sig4(acc[ai][bj][m][0] + bv[bj][0]), g1 * sig4(acc[ai][bj][m][1] + bv[bj][1])); } }
	v_pk_add_f32 v[140:141], v[140:141], v[84:85]
	v_pk_add_f32 v[142:143], v[142:143], v[86:87]
	v_mul_f32_e32 v201, 0xbfb8aa3b, v140
	v_mul_f32_e32 v216, 0xbfb8aa3b, v141
	v_pk_add_f32 v[138:139], v[138:139], v[82:83]
	v_pk_add_f32 v[136:137], v[136:137], v[80:81]
	v_mul_f32_e32 v217, 0xbfb8aa3b, v142
	v_mul_f32_e32 v220, 0xbfb8aa3b, v143
	v_exp_f32_e32 v201, v201
	v_exp_f32_e32 v216, v216
	v_pk_add_f32 v[132:133], v[132:133], v[68:69]
	v_mul_f32_e32 v221, 0xbfb8aa3b, v136
	v_mul_f32_e32 v222, 0xbfb8aa3b, v137
	v_mul_f32_e32 v223, 0xbfb8aa3b, v138
	v_mul_f32_e32 v224, 0xbfb8aa3b, v139
	v_exp_f32_e32 v217, v217
	v_exp_f32_e32 v220, v220
	v_pk_add_f32 v[134:135], v[134:135], v[70:71]
	v_pk_add_f32 v[128:129], v[128:129], v[64:65]
	v_pk_add_f32 v[130:131], v[130:131], v[66:67]
	v_mul_f32_e32 v132, 0xbfb8aa3b, v132
	v_exp_f32_e32 v221, v221
	v_exp_f32_e32 v222, v222
	v_exp_f32_e32 v223, v223
	v_exp_f32_e32 v224, v224
	v_mul_f32_e32 v133, 0xbfb8aa3b, v133
	v_mul_f32_e32 v134, 0xbfb8aa3b, v134
	v_mul_f32_e32 v135, 0xbfb8aa3b, v135
	v_mul_f32_e32 v128, 0xbfb8aa3b, v128
	v_mul_f32_e32 v129, 0xbfb8aa3b, v129
	v_mul_f32_e32 v130, 0xbfb8aa3b, v130
	v_mul_f32_e32 v131, 0xbfb8aa3b, v131
	v_exp_f32_e32 v132, v132
	v_exp_f32_e32 v133, v133
	v_exp_f32_e32 v134, v134
	v_exp_f32_e32 v135, v135
	v_exp_f32_e32 v128, v128
	v_exp_f32_e32 v129, v129
	v_exp_f32_e32 v130, v130
	v_exp_f32_e32 v131, v131
	v_pk_add_f32 v[124:125], v[124:125], v[84:85]
	v_lshlrev_b32_e32 v136, 16, v202
	v_and_b32_e32 v137, 0xffff0000, v202
	v_lshlrev_b32_e32 v138, 16, v203
	v_and_b32_e32 v139, 0xffff0000, v203
	v_lshlrev_b32_e32 v140, 16, v204
	v_and_b32_e32 v141, 0xffff0000, v204
	v_lshlrev_b32_e32 v142, 16, v205
	v_and_b32_e32 v143, 0xffff0000, v205
	v_lshlrev_b32_e32 v202, 16, v206
	v_and_b32_e32 v203, 0xffff0000, v206
	v_lshlrev_b32_e32 v204, 16, v207
	v_and_b32_e32 v205, 0xffff0000, v207
	v_lshlrev_b32_e32 v206, 16, v208
	v_and_b32_e32 v207, 0xffff0000, v208
	v_add_f32_e32 v201, 1.0, v201
	v_add_f32_e32 v208, 1.0, v216
	v_mul_f32_e32 v124, 0xbfb8aa3b, v124
	v_mul_f32_e32 v125, 0xbfb8aa3b, v125
	v_pk_add_f32 v[120:121], v[120:121], v[80:81]
	v_pk_add_f32 v[122:123], v[122:123], v[82:83]
	v_add_f32_e32 v225, 1.0, v217
	v_add_f32_e32 v226, 1.0, v220
	v_rcp_f32_e32 v216, v201
	v_rcp_f32_e32 v217, v208
	v_exp_f32_e32 v124, v124
	v_pk_add_f32 v[126:127], v[126:127], v[86:87]
	v_exp_f32_e32 v125, v125
	v_mul_f32_e32 v120, 0xbfb8aa3b, v120
	v_mul_f32_e32 v121, 0xbfb8aa3b, v121
	v_mul_f32_e32 v122, 0xbfb8aa3b, v122
	v_mul_f32_e32 v123, 0xbfb8aa3b, v123
	v_add_f32_e32 v227, 1.0, v221
	v_add_f32_e32 v228, 1.0, v222
	v_add_f32_e32 v223, 1.0, v223
	v_add_f32_e32 v229, 1.0, v224
	v_rcp_f32_e32 v220, v225
	v_rcp_f32_e32 v221, v226
	v_mul_f32_e32 v126, 0xbfb8aa3b, v126
	v_mul_f32_e32 v127, 0xbfb8aa3b, v127
	v_exp_f32_e32 v120, v120
	v_exp_f32_e32 v121, v121
	v_exp_f32_e32 v122, v122
	v_exp_f32_e32 v123, v123
	v_rcp_f32_e32 v222, v227
	v_rcp_f32_e32 v224, v223
	v_rcp_f32_e32 v225, v229
	v_rcp_f32_e32 v223, v228
	v_add_f32_e32 v132, 1.0, v132
	v_add_f32_e32 v133, 1.0, v133
	v_add_f32_e32 v134, 1.0, v134
	v_add_f32_e32 v135, 1.0, v135
	v_add_f32_e32 v128, 1.0, v128
	v_add_f32_e32 v129, 1.0, v129
	v_add_f32_e32 v130, 1.0, v130
	v_add_f32_e32 v131, 1.0, v131
	v_exp_f32_e32 v126, v126
	v_exp_f32_e32 v127, v127
	v_pk_add_f32 v[116:117], v[116:117], v[68:69]
	v_pk_add_f32 v[118:119], v[118:119], v[70:71]
	v_pk_add_f32 v[112:113], v[112:113], v[64:65]
	v_pk_add_f32 v[114:115], v[114:115], v[66:67]
	v_rcp_f32_e32 v132, v132
	v_rcp_f32_e32 v133, v133
	v_rcp_f32_e32 v134, v134
	v_rcp_f32_e32 v135, v135
	v_rcp_f32_e32 v128, v128
	v_rcp_f32_e32 v130, v130
	v_rcp_f32_e32 v131, v131
	v_rcp_f32_e32 v129, v129
	v_mul_f32_e32 v116, 0xbfb8aa3b, v116
	v_mul_f32_e32 v117, 0xbfb8aa3b, v117
	v_mul_f32_e32 v118, 0xbfb8aa3b, v118
	v_mul_f32_e32 v119, 0xbfb8aa3b, v119
	v_mul_f32_e32 v112, 0xbfb8aa3b, v112
	v_mul_f32_e32 v113, 0xbfb8aa3b, v113
	v_mul_f32_e32 v114, 0xbfb8aa3b, v114
	v_mul_f32_e32 v115, 0xbfb8aa3b, v115
	v_pk_mul_f32 v[136:137], v[216:217], v[136:137]
	v_add_f32_e32 v124, 1.0, v124
	v_add_f32_e32 v125, 1.0, v125
	v_exp_f32_e32 v116, v116
	v_exp_f32_e32 v117, v117
	v_exp_f32_e32 v118, v118
	v_exp_f32_e32 v119, v119
	v_exp_f32_e32 v112, v112
	v_exp_f32_e32 v113, v113
	v_exp_f32_e32 v114, v114
	v_exp_f32_e32 v115, v115
	v_pk_add_f32 v[108:109], v[108:109], v[84:85]
	v_pk_mul_f32 v[138:139], v[220:221], v[138:139]
	v_cvt_pk_bf16_f32 v136, v136, v137
	v_rcp_f32_e32 v124, v124
	v_cvt_pk_bf16_f32 v137, v138, v139
	v_rcp_f32_e32 v125, v125
	v_add_f32_e32 v120, 1.0, v120
	v_add_f32_e32 v121, 1.0, v121
	v_add_f32_e32 v122, 1.0, v122
	v_add_f32_e32 v123, 1.0, v123
	v_mul_f32_e32 v108, 0xbfb8aa3b, v108
	v_mul_f32_e32 v109, 0xbfb8aa3b, v109
	v_pk_add_f32 v[104:105], v[104:105], v[80:81]
	v_pk_add_f32 v[106:107], v[106:107], v[82:83]
	v_pk_mul_f32 v[142:143], v[224:225], v[142:143]
	v_pk_mul_f32 v[140:141], v[222:223], v[140:141]
	v_add_f32_e32 v126, 1.0, v126
	v_cvt_pk_bf16_f32 v138, v140, v141
	v_cvt_pk_bf16_f32 v139, v142, v143
	global_store_dwordx4 v[218:219], v[136:139], off sc1
	v_add_f32_e32 v127, 1.0, v127
	v_rcp_f32_e32 v120, v120
	v_lshlrev_b32_e32 v136, 16, v209
	v_and_b32_e32 v137, 0xffff0000, v209
	v_rcp_f32_e32 v122, v122
	v_rcp_f32_e32 v123, v123
	v_rcp_f32_e32 v121, v121
	v_exp_f32_e32 v108, v108
	v_pk_add_f32 v[110:111], v[110:111], v[86:87]
	v_exp_f32_e32 v109, v109
	v_mul_f32_e32 v104, 0xbfb8aa3b, v104
	v_mul_f32_e32 v105, 0xbfb8aa3b, v105
	v_mul_f32_e32 v106, 0xbfb8aa3b, v106
	v_mul_f32_e32 v107, 0xbfb8aa3b, v107
	v_pk_mul_f32 v[134:135], v[134:135], v[204:205]
	v_pk_mul_f32 v[132:133], v[132:133], v[202:203]
; __device__ __forceinline__ u32x4 pack8(const f32x4 v0, const f32x4 v1) { u32x4 w; w.x = cvt_pk_bf16(v0[0], v0[1]); w.y = cvt_pk_bf16(v0[2], v0[3]); w.z = cvt_pk_bf16(v1[0], v1[1]); w.w = cvt_pk_bf16(v1[2], v1[3]); return w; }
; __device__ __forceinline__ void unpack8(const u32x4 w, f32x4& v0, f32x4& v1) { v0 = (f32x4){bflo(w.x), bfhi(w.x), bflo(w.y), bfhi(w.y)}; v1 = (f32x4){bflo(w.z), bfhi(w.z), bflo(w.w), bfhi(w.w)}; }
; __device__ __forceinline__ f32x4 sig4(const f32x4 v) { return (f32x4){sigmoidf_(v[0]), sigmoidf_(v[1]), sigmoidf_(v[2]), sigmoidf_(v[3])}; }
;     __device__ __forceinline__ void operator()(const AccT& acc, const pg8::Unit& u, int wr, int wc, int fr, int fq) const {
;     ...
;         for (int ai = 0; ai < 2; ++ai) { u32x4 gw[4][2];
; #pragma unroll
;             for (int m = 0; m < 4; ++m)
; #pragma unroll
;                 for (int bj = 0; bj < 2; ++bj) gw[m][bj] = *(const u32x4*)(G + (size_t)(row0 + ai * 128 + m * 16) * 1024 + col0 + bj * 128);
; #pragma unroll
;             for (int m = 0; m < 4; ++m)
; #pragma unroll
;                 for (int bj = 0; bj < 2; ++bj) { f32x4 g0, g1; unpack8(gw[m][bj], g0, g1);
;                     *(u32x4*)(O + (size_t)(row0 + ai * 128 + m * 16) * 1024 + col0 + bj * 128) = pack8(g0 * sig4(acc[ai][bj][m][0] + bv[bj][0]), g1 * sig4(acc[ai][bj][m][1] + bv[bj][1])); } }
	v_pk_mul_f32 v[136:137], v[130:131], v[136:137]
	v_pk_mul_f32 v[130:131], v[128:129], v[206:207]
	v_cvt_pk_bf16_f32 v128, v132, v133
	v_cvt_pk_bf16_f32 v129, v134, v135
	v_rcp_f32_e32 v126, v126
	v_rcp_f32_e32 v127, v127
	v_mul_f32_e32 v110, 0xbfb8aa3b, v110
	v_mul_f32_e32 v111, 0xbfb8aa3b, v111
	v_exp_f32_e32 v104, v104
	v_exp_f32_e32 v105, v105
	v_exp_f32_e32 v106, v106
	v_exp_f32_e32 v107, v107
	v_cvt_pk_bf16_f32 v130, v130, v131
	v_cvt_pk_bf16_f32 v131, v136, v137
	global_store_dwordx4 v[218:219], v[128:131], off offset:256 sc1
	v_add_f32_e32 v116, 1.0, v116
	v_add_f32_e32 v117, 1.0, v117
	v_lshlrev_b32_e32 v128, 16, v210
	v_and_b32_e32 v129, 0xffff0000, v210
	v_add_f32_e32 v118, 1.0, v118
	v_add_f32_e32 v119, 1.0, v119
	v_add_f32_e32 v112, 1.0, v112
	v_add_f32_e32 v113, 1.0, v113
	v_add_f32_e32 v114, 1.0, v114
	v_add_f32_e32 v115, 1.0, v115
	v_exp_f32_e32 v110, v110
	v_exp_f32_e32 v111, v111
	v_pk_add_f32 v[100:101], v[100:101], v[68:69]
	v_pk_add_f32 v[102:103], v[102:103], v[70:71]
	v_pk_add_f32 v[96:97], v[96:97], v[64:65]
	v_pk_add_f32 v[98:99], v[98:99], v[66:67]
	v_lshlrev_b32_e32 v132, 16, v212
	v_and_b32_e32 v133, 0xffff0000, v212
	v_lshlrev_b32_e32 v134, 16, v213
	v_and_b32_e32 v135, 0xffff0000, v213
	v_pk_mul_f32 v[124:125], v[124:125], v[128:129]
	v_rcp_f32_e32 v116, v116
	v_rcp_f32_e32 v117, v117
	v_rcp_f32_e32 v118, v118
	v_rcp_f32_e32 v119, v119
	v_rcp_f32_e32 v112, v112
	v_rcp_f32_e32 v114, v114
	v_rcp_f32_e32 v115, v115
	v_rcp_f32_e32 v113, v113
	v_mul_f32_e32 v100, 0xbfb8aa3b, v100
	v_mul_f32_e32 v101, 0xbfb8aa3b, v101
	v_mul_f32_e32 v102, 0xbfb8aa3b, v102
	v_mul_f32_e32 v103, 0xbfb8aa3b, v103
	v_mul_f32_e32 v96, 0xbfb8aa3b, v96
	v_mul_f32_e32 v97, 0xbfb8aa3b, v97
	v_mul_f32_e32 v98, 0xbfb8aa3b, v98
	v_mul_f32_e32 v99, 0xbfb8aa3b, v99
	v_lshlrev_b32_e32 v130, 16, v211
	v_and_b32_e32 v131, 0xffff0000, v211
	v_pk_mul_f32 v[128:129], v[122:123], v[134:135]
	v_pk_mul_f32 v[122:123], v[120:121], v[132:133]
	v_cvt_pk_bf16_f32 v120, v124, v125
	v_lshl_add_u64 v[124:125], s[4:5], 0, v[190:191]
	v_add_f32_e32 v108, 1.0, v108
	v_add_f32_e32 v109, 1.0, v109
	v_exp_f32_e32 v100, v100
	v_exp_f32_e32 v101, v101
	v_exp_f32_e32 v102, v102
	v_exp_f32_e32 v103, v103
	v_exp_f32_e32 v96, v96
	v_exp_f32_e32 v97, v97
	v_exp_f32_e32 v98, v98
	v_exp_f32_e32 v99, v99
	v_pk_add_f32 v[92:93], v[92:93], v[84:85]
	v_pk_mul_f32 v[126:127], v[126:127], v[130:131]
	v_lshl_add_u64 v[124:125], v[124:125], 0, v[180:181]
	v_cvt_pk_bf16_f32 v121, v126, v127
	v_cvt_pk_bf16_f32 v122, v122, v123
	v_cvt_pk_bf16_f32 v123, v128, v129
	v_rcp_f32_e32 v108, v108
	v_rcp_f32_e32 v109, v109
	v_add_f32_e32 v104, 1.0, v104
	v_add_f32_e32 v105, 1.0, v105
	v_add_f32_e32 v106, 1.0, v106
	v_add_f32_e32 v107, 1.0, v107
	v_mul_f32_e32 v92, 0xbfb8aa3b, v92
	v_mul_f32_e32 v93, 0xbfb8aa3b, v93
	v_pk_add_f32 v[88:89], v[88:89], v[80:81]
	v_pk_add_f32 v[90:91], v[90:91], v[82:83]
	global_store_dwordx4 v[124:125], v[120:123], off sc1
	v_lshlrev_b32_e32 v126, 16, v162
	v_and_b32_e32 v127, 0xffff0000, v162
	v_lshlrev_b32_e32 v120, 16, v160
	v_and_b32_e32 v121, 0xffff0000, v160
	v_lshlrev_b32_e32 v122, 16, v161
	v_and_b32_e32 v123, 0xffff0000, v161
	v_lshlrev_b32_e32 v128, 16, v163
	v_and_b32_e32 v129, 0xffff0000, v163
	v_add_f32_e32 v110, 1.0, v110
	v_add_f32_e32 v111, 1.0, v111
	v_rcp_f32_e32 v104, v104
	v_rcp_f32_e32 v106, v106
	v_rcp_f32_e32 v107, v107
	v_rcp_f32_e32 v105, v105
	v_exp_f32_e32 v92, v92
	v_pk_add_f32 v[94:95], v[94:95], v[86:87]
	v_exp_f32_e32 v93, v93
	v_mul_f32_e32 v88, 0xbfb8aa3b, v88
	v_mul_f32_e32 v89, 0xbfb8aa3b, v89
	v_mul_f32_e32 v90, 0xbfb8aa3b, v90
	v_mul_f32_e32 v91, 0xbfb8aa3b, v91
	v_pk_mul_f32 v[118:119], v[118:119], v[122:123]
	v_pk_mul_f32 v[116:117], v[116:117], v[120:121]
	v_pk_mul_f32 v[120:121], v[114:115], v[128:129]
	v_pk_mul_f32 v[114:115], v[112:113], v[126:127]
	v_cvt_pk_bf16_f32 v112, v116, v117
	v_cvt_pk_bf16_f32 v113, v118, v119
	v_rcp_f32_e32 v110, v110
	v_rcp_f32_e32 v111, v111
	v_mul_f32_e32 v94, 0xbfb8aa3b, v94
	v_mul_f32_e32 v95, 0xbfb8aa3b, v95
	v_exp_f32_e32 v88, v88
	v_exp_f32_e32 v89, v89
	v_exp_f32_e32 v90, v90
	v_exp_f32_e32 v91, v91
	v_cvt_pk_bf16_f32 v114, v114, v115
	v_cvt_pk_bf16_f32 v115, v120, v121
	global_store_dwordx4 v[124:125], v[112:115], off offset:256 sc1
	v_add_f32_e32 v100, 1.0, v100
	v_add_f32_e32 v101, 1.0, v101
	v_lshlrev_b32_e32 v112, 16, v156
	v_and_b32_e32 v113, 0xffff0000, v156
	v_add_f32_e32 v102, 1.0, v102
	v_add_f32_e32 v103, 1.0, v103
	v_add_f32_e32 v96, 1.0, v96
	v_add_f32_e32 v97, 1.0, v97
	v_add_f32_e32 v98, 1.0, v98
	v_add_f32_e32 v99, 1.0, v99
	v_exp_f32_e32 v94, v94
	v_exp_f32_e32 v95, v95
	v_pk_add_f32 v[76:77], v[76:77], v[68:69]
	v_lshlrev_b32_e32 v116, 16, v158
	v_and_b32_e32 v117, 0xffff0000, v158
	v_lshlrev_b32_e32 v118, 16, v159
	v_and_b32_e32 v119, 0xffff0000, v159
	v_pk_mul_f32 v[108:109], v[108:109], v[112:113]
	v_rcp_f32_e32 v100, v100
	v_rcp_f32_e32 v101, v101
	v_rcp_f32_e32 v102, v102
	v_rcp_f32_e32 v103, v103
	v_rcp_f32_e32 v96, v96
	v_rcp_f32_e32 v98, v98
	v_rcp_f32_e32 v99, v99
	v_rcp_f32_e32 v97, v97
	v_mul_f32_e32 v76, 0xbfb8aa3b, v76
	v_mul_f32_e32 v77, 0xbfb8aa3b, v77
	v_pk_add_f32 v[72:73], v[72:73], v[64:65]
	v_pk_add_f32 v[74:75], v[74:75], v[66:67]
	v_lshlrev_b32_e32 v114, 16, v157
	v_and_b32_e32 v115, 0xffff0000, v157
	v_pk_mul_f32 v[112:113], v[106:107], v[118:119]
	v_pk_mul_f32 v[106:107], v[104:105], v[116:117]
	v_cvt_pk_bf16_f32 v104, v108, v109
	v_lshl_add_u64 v[108:109], s[4:5], 0, v[188:189]
	v_add_f32_e32 v92, 1.0, v92
	v_add_f32_e32 v93, 1.0, v93
	v_exp_f32_e32 v76, v76
	v_pk_add_f32 v[78:79], v[78:79], v[70:71]
	v_exp_f32_e32 v77, v77
	v_mul_f32_e32 v72, 0xbfb8aa3b, v72
; __device__ __forceinline__ u32x4 pack8(const f32x4 v0, const f32x4 v1) { u32x4 w; w.x = cvt_pk_bf16(v0[0], v0[1]); w.y = cvt_pk_bf16(v0[2], v0[3]); w.z = cvt_pk_bf16(v1[0], v1[1]); w.w = cvt_pk_bf16(v1[2], v1[3]); return w; }
; __device__ __forceinline__ void unpack8(const u32x4 w, f32x4& v0, f32x4& v1) { v0 = (f32x4){bflo(w.x), bfhi(w.x), bflo(w.y), bfhi(w.y)}; v1 = (f32x4){bflo(w.z), bfhi(w.z), bflo(w.w), bfhi(w.w)}; }
; __device__ __forceinline__ f32x4 sig4(const f32x4 v) { return (f32x4){sigmoidf_(v[0]), sigmoidf_(v[1]), sigmoidf_(v[2]), sigmoidf_(v[3])}; }
;     __device__ __forceinline__ void operator()(const AccT& acc, const pg8::Unit& u, int wr, int wc, int fr, int fq) const {
;     ...
;         for (int ai = 0; ai < 2; ++ai) { u32x4 gw[4][2];
; #pragma unroll
;             for (int m = 0; m < 4; ++m)
; #pragma unroll
;                 for (int bj = 0; bj < 2; ++bj) gw[m][bj] = *(const u32x4*)(G + (size_t)(row0 + ai * 128 + m * 16) * 1024 + col0 + bj * 128);
; #pragma unroll
;             for (int m = 0; m < 4; ++m)
; #pragma unroll
;                 for (int bj = 0; bj < 2; ++bj) { f32x4 g0, g1; unpack8(gw[m][bj], g0, g1);
;                     *(u32x4*)(O + (size_t)(row0 + ai * 128 + m * 16) * 1024 + col0 + bj * 128) = pack8(g0 * sig4(acc[ai][bj][m][0] + bv[bj][0]), g1 * sig4(acc[ai][bj][m][1] + bv[bj][1])); } }
	v_mul_f32_e32 v73, 0xbfb8aa3b, v73
	v_mul_f32_e32 v74, 0xbfb8aa3b, v74
	v_mul_f32_e32 v75, 0xbfb8aa3b, v75
	v_pk_mul_f32 v[110:111], v[110:111], v[114:115]
	v_lshl_add_u64 v[108:109], v[108:109], 0, v[180:181]
	v_cvt_pk_bf16_f32 v105, v110, v111
	v_cvt_pk_bf16_f32 v106, v106, v107
	v_cvt_pk_bf16_f32 v107, v112, v113
	v_rcp_f32_e32 v92, v92
	v_rcp_f32_e32 v93, v93
	v_add_f32_e32 v88, 1.0, v88
	v_add_f32_e32 v89, 1.0, v89
	v_add_f32_e32 v90, 1.0, v90
	v_add_f32_e32 v91, 1.0, v91
	v_mul_f32_e32 v78, 0xbfb8aa3b, v78
	v_mul_f32_e32 v79, 0xbfb8aa3b, v79
	v_exp_f32_e32 v72, v72
	v_exp_f32_e32 v73, v73
	v_exp_f32_e32 v74, v74
	v_exp_f32_e32 v75, v75
	global_store_dwordx4 v[108:109], v[104:107], off sc1
	v_lshlrev_b32_e32 v110, 16, v154
	v_and_b32_e32 v111, 0xffff0000, v154
	v_lshlrev_b32_e32 v104, 16, v152
	v_and_b32_e32 v105, 0xffff0000, v152
	v_lshlrev_b32_e32 v106, 16, v153
	v_and_b32_e32 v107, 0xffff0000, v153
	v_lshlrev_b32_e32 v112, 16, v155
	v_and_b32_e32 v113, 0xffff0000, v155
	v_add_f32_e32 v94, 1.0, v94
	v_add_f32_e32 v95, 1.0, v95
	v_rcp_f32_e32 v88, v88
	v_rcp_f32_e32 v90, v90
	v_rcp_f32_e32 v91, v91
	v_rcp_f32_e32 v89, v89
	v_exp_f32_e32 v78, v78
	v_exp_f32_e32 v79, v79
	v_pk_mul_f32 v[102:103], v[102:103], v[106:107]
	v_pk_mul_f32 v[100:101], v[100:101], v[104:105]
	v_pk_mul_f32 v[104:105], v[98:99], v[112:113]
	v_pk_mul_f32 v[98:99], v[96:97], v[110:111]
	v_cvt_pk_bf16_f32 v96, v100, v101
	v_cvt_pk_bf16_f32 v97, v102, v103
	v_rcp_f32_e32 v94, v94
	v_rcp_f32_e32 v95, v95
	v_cvt_pk_bf16_f32 v98, v98, v99
	v_cvt_pk_bf16_f32 v99, v104, v105
	global_store_dwordx4 v[108:109], v[96:99], off offset:256 sc1
	v_add_f32_e32 v76, 1.0, v76
	v_add_f32_e32 v77, 1.0, v77
	v_lshlrev_b32_e32 v96, 16, v148
	v_and_b32_e32 v97, 0xffff0000, v148
	v_lshlrev_b32_e32 v100, 16, v150
	v_and_b32_e32 v101, 0xffff0000, v150
	v_lshlrev_b32_e32 v102, 16, v151
	v_and_b32_e32 v103, 0xffff0000, v151
	v_pk_mul_f32 v[92:93], v[92:93], v[96:97]
	v_rcp_f32_e32 v76, v76
	v_rcp_f32_e32 v77, v77
	v_add_f32_e32 v72, 1.0, v72
	v_add_f32_e32 v73, 1.0, v73
	v_add_f32_e32 v74, 1.0, v74
	v_add_f32_e32 v75, 1.0, v75
	v_lshlrev_b32_e32 v98, 16, v149
	v_and_b32_e32 v99, 0xffff0000, v149
	v_pk_mul_f32 v[96:97], v[90:91], v[102:103]
	v_pk_mul_f32 v[90:91], v[88:89], v[100:101]
	v_cvt_pk_bf16_f32 v88, v92, v93
	v_lshl_add_u64 v[92:93], s[4:5], 0, v[186:187]
	v_add_f32_e32 v78, 1.0, v78
	v_add_f32_e32 v79, 1.0, v79
	v_rcp_f32_e32 v72, v72
	v_rcp_f32_e32 v74, v74
	v_rcp_f32_e32 v75, v75
	v_rcp_f32_e32 v73, v73
	v_pk_mul_f32 v[94:95], v[94:95], v[98:99]
	v_lshl_add_u64 v[92:93], v[92:93], 0, v[180:181]
	v_cvt_pk_bf16_f32 v89, v94, v95
	v_rcp_f32_e32 v78, v78
	v_rcp_f32_e32 v79, v79
	v_cvt_pk_bf16_f32 v90, v90, v91
	v_cvt_pk_bf16_f32 v91, v96, v97
	global_store_dwordx4 v[92:93], v[88:91], off sc1
	v_lshlrev_b32_e32 v94, 16, v146
	v_and_b32_e32 v95, 0xffff0000, v146
	v_lshlrev_b32_e32 v88, 16, v144
	v_and_b32_e32 v89, 0xffff0000, v144
	v_lshlrev_b32_e32 v96, 16, v147
	v_and_b32_e32 v97, 0xffff0000, v147
	v_pk_mul_f32 v[76:77], v[76:77], v[88:89]
	v_lshl_add_u64 v[118:119], v[184:185], 0, s[0:1]
	v_lshlrev_b32_e32 v90, 16, v145
	v_and_b32_e32 v91, 0xffff0000, v145
	v_pk_mul_f32 v[88:89], v[74:75], v[96:97]
	v_pk_mul_f32 v[74:75], v[72:73], v[94:95]
	v_cvt_pk_bf16_f32 v72, v76, v77
	v_lshl_add_u64 v[76:77], v[182:183], 0, v[118:119]
	v_pk_mul_f32 v[78:79], v[78:79], v[90:91]
	v_lshl_add_u64 v[104:105], v[184:185], 0, s[16:17]
	v_cvt_pk_bf16_f32 v73, v78, v79
	v_cvt_pk_bf16_f32 v74, v74, v75
	v_cvt_pk_bf16_f32 v75, v88, v89
	global_load_dwordx4 v[106:109], v[76:77], off
	global_load_dwordx4 v[110:113], v[76:77], off offset:256
	v_lshl_add_u64 v[102:103], v[184:185], 0, s[18:19]
	global_store_dwordx4 v[92:93], v[72:75], off offset:256 sc1
	v_lshl_add_u64 v[100:101], v[184:185], 0, s[20:21]
	v_pk_add_f32 v[60:61], v[60:61], v[84:85]
	v_lshl_add_u64 v[72:73], v[182:183], 0, v[104:105]
	global_load_dwordx4 v[114:117], v[72:73], off
	global_load_dwordx4 v[96:99], v[72:73], off offset:256
	v_lshl_add_u64 v[72:73], v[182:183], 0, v[102:103]
	global_load_dwordx4 v[92:95], v[72:73], off
	global_load_dwordx4 v[88:91], v[72:73], off offset:256
	v_lshl_add_u64 v[72:73], v[182:183], 0, v[100:101]
	global_load_dwordx4 v[76:79], v[72:73], off
	s_nop 0
	global_load_dwordx4 v[72:75], v[72:73], off offset:256
	v_mul_f32_e32 v60, 0xbfb8aa3b, v60
	v_pk_add_f32 v[62:63], v[62:63], v[86:87]
	v_mul_f32_e32 v61, 0xbfb8aa3b, v61
	v_pk_add_f32 v[56:57], v[56:57], v[80:81]
	v_pk_add_f32 v[58:59], v[58:59], v[82:83]
	v_exp_f32_e32 v60, v60
	v_exp_f32_e32 v61, v61
	v_mul_f32_e32 v62, 0xbfb8aa3b, v62
	v_mul_f32_e32 v63, 0xbfb8aa3b, v63
	v_mul_f32_e32 v56, 0xbfb8aa3b, v56
	v_mul_f32_e32 v57, 0xbfb8aa3b, v57
	v_mul_f32_e32 v58, 0xbfb8aa3b, v58
	v_mul_f32_e32 v59, 0xbfb8aa3b, v59
	v_exp_f32_e32 v62, v62
	v_exp_f32_e32 v63, v63
	v_exp_f32_e32 v56, v56
	v_exp_f32_e32 v57, v57
	v_exp_f32_e32 v58, v58
	v_exp_f32_e32 v59, v59
	v_pk_add_f32 v[52:53], v[52:53], v[68:69]
	v_pk_add_f32 v[54:55], v[54:55], v[70:71]
	v_pk_add_f32 v[48:49], v[48:49], v[64:65]
	v_pk_add_f32 v[50:51], v[50:51], v[66:67]
	v_mul_f32_e32 v52, 0xbfb8aa3b, v52
	v_mul_f32_e32 v53, 0xbfb8aa3b, v53
	v_mul_f32_e32 v54, 0xbfb8aa3b, v54
	v_mul_f32_e32 v55, 0xbfb8aa3b, v55
	v_mul_f32_e32 v48, 0xbfb8aa3b, v48
	v_mul_f32_e32 v49, 0xbfb8aa3b, v49
	v_mul_f32_e32 v50, 0xbfb8aa3b, v50
	v_mul_f32_e32 v51, 0xbfb8aa3b, v51
	v_add_f32_e32 v60, 1.0, v60
	v_add_f32_e32 v61, 1.0, v61
	v_exp_f32_e32 v52, v52
	v_exp_f32_e32 v53, v53
	v_exp_f32_e32 v54, v54
	v_exp_f32_e32 v55, v55
	v_exp_f32_e32 v48, v48
	v_exp_f32_e32 v49, v49
	v_exp_f32_e32 v50, v50
	v_exp_f32_e32 v51, v51
	v_pk_add_f32 v[44:45], v[44:45], v[84:85]
	v_rcp_f32_e32 v60, v60
	v_rcp_f32_e32 v61, v61
	v_add_f32_e32 v62, 1.0, v62
	v_add_f32_e32 v63, 1.0, v63
	v_add_f32_e32 v56, 1.0, v56
	v_add_f32_e32 v57, 1.0, v57
	v_add_f32_e32 v58, 1.0, v58
	v_add_f32_e32 v59, 1.0, v59
	v_mul_f32_e32 v44, 0xbfb8aa3b, v44
	v_mul_f32_e32 v45, 0xbfb8aa3b, v45
	v_pk_add_f32 v[40:41], v[40:41], v[80:81]
	v_pk_add_f32 v[42:43], v[42:43], v[82:83]
	v_rcp_f32_e32 v62, v62
	v_rcp_f32_e32 v63, v63
	v_rcp_f32_e32 v56, v56
	v_rcp_f32_e32 v58, v58
	v_rcp_f32_e32 v59, v59
	v_rcp_f32_e32 v57, v57
	v_exp_f32_e32 v44, v44
	v_pk_add_f32 v[46:47], v[46:47], v[86:87]
	v_exp_f32_e32 v45, v45
	v_mul_f32_e32 v40, 0xbfb8aa3b, v40
	v_mul_f32_e32 v41, 0xbfb8aa3b, v41
	v_mul_f32_e32 v42, 0xbfb8aa3b, v42
	v_mul_f32_e32 v43, 0xbfb8aa3b, v43
	v_mul_f32_e32 v46, 0xbfb8aa3b, v46
	v_mul_f32_e32 v47, 0xbfb8aa3b, v47
	v_exp_f32_e32 v40, v40
	v_exp_f32_e32 v41, v41
	v_exp_f32_e32 v42, v42
	v_exp_f32_e32 v43, v43
	s_waitcnt vmcnt(0)
; __device__ __forceinline__ u32x4 pack8(const f32x4 v0, const f32x4 v1) { u32x4 w; w.x = cvt_pk_bf16(v0[0], v0[1]); w.y = cvt_pk_bf16(v0[2], v0[3]); w.z = cvt_pk_bf16(v1[0], v1[1]); w.w = cvt_pk_bf16(v1[2], v1[3]); return w; }
; __device__ __forceinline__ void unpack8(const u32x4 w, f32x4& v0, f32x4& v1) { v0 = (f32x4){bflo(w.x), bfhi(w.x), bflo(w.y), bfhi(w.y)}; v1 = (f32x4){bflo(w.z), bfhi(w.z), bflo(w.w), bfhi(w.w)}; }
; __device__ __forceinline__ f32x4 sig4(const f32x4 v) { return (f32x4){sigmoidf_(v[0]), sigmoidf_(v[1]), sigmoidf_(v[2]), sigmoidf_(v[3])}; }
;     __device__ __forceinline__ void operator()(const AccT& acc, const pg8::Unit& u, int wr, int wc, int fr, int fq) const {
;     ...
;         for (int ai = 0; ai < 2; ++ai) { u32x4 gw[4][2];
; #pragma unroll
;             for (int m = 0; m < 4; ++m)
; #pragma unroll
;                 for (int bj = 0; bj < 2; ++bj) gw[m][bj] = *(const u32x4*)(G + (size_t)(row0 + ai * 128 + m * 16) * 1024 + col0 + bj * 128);
; #pragma unroll
;             for (int m = 0; m < 4; ++m)
; #pragma unroll
;                 for (int bj = 0; bj < 2; ++bj) { f32x4 g0, g1; unpack8(gw[m][bj], g0, g1);
;                     *(u32x4*)(O + (size_t)(row0 + ai * 128 + m * 16) * 1024 + col0 + bj * 128) = pack8(g0 * sig4(acc[ai][bj][m][0] + bv[bj][0]), g1 * sig4(acc[ai][bj][m][1] + bv[bj][1])); } }
	v_lshlrev_b32_e32 v120, 16, v106
	v_and_b32_e32 v121, 0xffff0000, v106
	v_add_f32_e32 v52, 1.0, v52
	v_add_f32_e32 v53, 1.0, v53
	v_add_f32_e32 v54, 1.0, v54
	v_add_f32_e32 v55, 1.0, v55
	v_add_f32_e32 v48, 1.0, v48
	v_add_f32_e32 v49, 1.0, v49
	v_add_f32_e32 v50, 1.0, v50
	v_add_f32_e32 v51, 1.0, v51
	v_exp_f32_e32 v46, v46
	v_exp_f32_e32 v47, v47
	v_pk_add_f32 v[36:37], v[36:37], v[68:69]
	v_pk_add_f32 v[38:39], v[38:39], v[70:71]
	v_pk_add_f32 v[32:33], v[32:33], v[64:65]
	v_pk_add_f32 v[34:35], v[34:35], v[66:67]
	v_lshlrev_b32_e32 v106, 16, v107
	v_and_b32_e32 v107, 0xffff0000, v107
	v_lshlrev_b32_e32 v122, 16, v108
	v_and_b32_e32 v123, 0xffff0000, v108
	v_lshlrev_b32_e32 v108, 16, v109
	v_and_b32_e32 v109, 0xffff0000, v109
	v_pk_mul_f32 v[60:61], v[60:61], v[120:121]
	v_rcp_f32_e32 v52, v52
	v_rcp_f32_e32 v53, v53
	v_rcp_f32_e32 v54, v54
	v_rcp_f32_e32 v55, v55
	v_rcp_f32_e32 v48, v48
	v_rcp_f32_e32 v50, v50
	v_rcp_f32_e32 v51, v51
	v_rcp_f32_e32 v49, v49
	v_mul_f32_e32 v36, 0xbfb8aa3b, v36
	v_mul_f32_e32 v37, 0xbfb8aa3b, v37
	v_mul_f32_e32 v38, 0xbfb8aa3b, v38
	v_mul_f32_e32 v39, 0xbfb8aa3b, v39
	v_mul_f32_e32 v32, 0xbfb8aa3b, v32
	v_mul_f32_e32 v33, 0xbfb8aa3b, v33
	v_mul_f32_e32 v34, 0xbfb8aa3b, v34
	v_mul_f32_e32 v35, 0xbfb8aa3b, v35
	v_pk_mul_f32 v[62:63], v[62:63], v[106:107]
	v_pk_mul_f32 v[106:107], v[58:59], v[108:109]
	v_pk_mul_f32 v[58:59], v[56:57], v[122:123]
	v_cvt_pk_bf16_f32 v56, v60, v61
	v_lshl_add_u64 v[60:61], s[4:5], 0, v[118:119]
	v_add_f32_e32 v44, 1.0, v44
	v_add_f32_e32 v45, 1.0, v45
	v_exp_f32_e32 v36, v36
	v_exp_f32_e32 v37, v37
	v_exp_f32_e32 v38, v38
	v_exp_f32_e32 v39, v39
	v_exp_f32_e32 v32, v32
	v_exp_f32_e32 v33, v33
	v_exp_f32_e32 v34, v34
	v_exp_f32_e32 v35, v35
	v_pk_add_f32 v[28:29], v[28:29], v[84:85]
	v_cvt_pk_bf16_f32 v57, v62, v63
	v_cvt_pk_bf16_f32 v58, v58, v59
	v_cvt_pk_bf16_f32 v59, v106, v107
	v_lshl_add_u64 v[60:61], v[60:61], 0, v[180:181]
	v_rcp_f32_e32 v44, v44
	v_rcp_f32_e32 v45, v45
	v_add_f32_e32 v40, 1.0, v40
	v_add_f32_e32 v41, 1.0, v41
	v_add_f32_e32 v42, 1.0, v42
	v_add_f32_e32 v43, 1.0, v43
	v_mul_f32_e32 v28, 0xbfb8aa3b, v28
	v_mul_f32_e32 v29, 0xbfb8aa3b, v29
	v_pk_add_f32 v[24:25], v[24:25], v[80:81]
	v_pk_add_f32 v[26:27], v[26:27], v[82:83]
	global_store_dwordx4 v[60:61], v[56:59], off sc1
	v_lshlrev_b32_e32 v62, 16, v112
	v_and_b32_e32 v63, 0xffff0000, v112
	v_lshlrev_b32_e32 v56, 16, v110
	v_and_b32_e32 v57, 0xffff0000, v110
	v_lshlrev_b32_e32 v58, 16, v111
	v_and_b32_e32 v59, 0xffff0000, v111
	v_lshlrev_b32_e32 v106, 16, v113
	v_and_b32_e32 v107, 0xffff0000, v113
	v_add_f32_e32 v46, 1.0, v46
	v_add_f32_e32 v47, 1.0, v47
	v_rcp_f32_e32 v40, v40
	v_rcp_f32_e32 v42, v42
	v_rcp_f32_e32 v43, v43
	v_rcp_f32_e32 v41, v41
	v_exp_f32_e32 v28, v28
	v_pk_add_f32 v[30:31], v[30:31], v[86:87]
	v_exp_f32_e32 v29, v29
	v_mul_f32_e32 v24, 0xbfb8aa3b, v24
	v_mul_f32_e32 v25, 0xbfb8aa3b, v25
	v_mul_f32_e32 v26, 0xbfb8aa3b, v26
	v_mul_f32_e32 v27, 0xbfb8aa3b, v27
	v_pk_mul_f32 v[54:55], v[54:55], v[58:59]
	v_pk_mul_f32 v[52:53], v[52:53], v[56:57]
	v_pk_mul_f32 v[56:57], v[50:51], v[106:107]
	v_pk_mul_f32 v[50:51], v[48:49], v[62:63]
	v_cvt_pk_bf16_f32 v48, v52, v53
	v_cvt_pk_bf16_f32 v49, v54, v55
	v_rcp_f32_e32 v46, v46
	v_rcp_f32_e32 v47, v47
	v_mul_f32_e32 v30, 0xbfb8aa3b, v30
	v_mul_f32_e32 v31, 0xbfb8aa3b, v31
	v_exp_f32_e32 v24, v24
	v_exp_f32_e32 v25, v25
	v_exp_f32_e32 v26, v26
	v_exp_f32_e32 v27, v27
	v_cvt_pk_bf16_f32 v50, v50, v51
	v_cvt_pk_bf16_f32 v51, v56, v57
	global_store_dwordx4 v[60:61], v[48:51], off offset:256 sc1
	v_add_f32_e32 v36, 1.0, v36
	v_add_f32_e32 v37, 1.0, v37
	v_lshlrev_b32_e32 v48, 16, v114
	v_and_b32_e32 v49, 0xffff0000, v114
	v_add_f32_e32 v38, 1.0, v38
	v_add_f32_e32 v39, 1.0, v39
	v_add_f32_e32 v32, 1.0, v32
	v_add_f32_e32 v33, 1.0, v33
	v_add_f32_e32 v34, 1.0, v34
	v_add_f32_e32 v35, 1.0, v35
	v_exp_f32_e32 v30, v30
	v_exp_f32_e32 v31, v31
	v_pk_add_f32 v[20:21], v[20:21], v[68:69]
	v_pk_add_f32 v[22:23], v[22:23], v[70:71]
	v_pk_add_f32 v[16:17], v[16:17], v[64:65]
	v_pk_add_f32 v[18:19], v[18:19], v[66:67]
	v_lshlrev_b32_e32 v52, 16, v116
	v_and_b32_e32 v53, 0xffff0000, v116
	v_lshlrev_b32_e32 v54, 16, v117
	v_and_b32_e32 v55, 0xffff0000, v117
	v_pk_mul_f32 v[44:45], v[44:45], v[48:49]
	v_rcp_f32_e32 v36, v36
	v_rcp_f32_e32 v37, v37
	v_rcp_f32_e32 v38, v38
	v_rcp_f32_e32 v39, v39
	v_rcp_f32_e32 v32, v32
	v_rcp_f32_e32 v34, v34
	v_rcp_f32_e32 v35, v35
	v_rcp_f32_e32 v33, v33
	v_mul_f32_e32 v20, 0xbfb8aa3b, v20
	v_mul_f32_e32 v21, 0xbfb8aa3b, v21
	v_mul_f32_e32 v22, 0xbfb8aa3b, v22
	v_mul_f32_e32 v23, 0xbfb8aa3b, v23
	v_mul_f32_e32 v16, 0xbfb8aa3b, v16
	v_mul_f32_e32 v17, 0xbfb8aa3b, v17
	v_mul_f32_e32 v18, 0xbfb8aa3b, v18
	v_mul_f32_e32 v19, 0xbfb8aa3b, v19
	v_lshlrev_b32_e32 v50, 16, v115
	v_and_b32_e32 v51, 0xffff0000, v115
	v_pk_mul_f32 v[48:49], v[42:43], v[54:55]
	v_pk_mul_f32 v[42:43], v[40:41], v[52:53]
	v_cvt_pk_bf16_f32 v40, v44, v45
	v_lshl_add_u64 v[44:45], s[4:5], 0, v[104:105]
	v_add_f32_e32 v28, 1.0, v28
	v_add_f32_e32 v29, 1.0, v29
	v_exp_f32_e32 v20, v20
	v_exp_f32_e32 v21, v21
	v_exp_f32_e32 v22, v22
	v_exp_f32_e32 v23, v23
	v_exp_f32_e32 v16, v16
	v_exp_f32_e32 v17, v17
	v_exp_f32_e32 v18, v18
	v_exp_f32_e32 v19, v19
	v_pk_add_f32 v[12:13], v[12:13], v[84:85]
	v_pk_mul_f32 v[46:47], v[46:47], v[50:51]
	v_lshl_add_u64 v[44:45], v[44:45], 0, v[180:181]
	v_cvt_pk_bf16_f32 v41, v46, v47
	v_cvt_pk_bf16_f32 v42, v42, v43
	v_cvt_pk_bf16_f32 v43, v48, v49
	v_rcp_f32_e32 v28, v28
	v_rcp_f32_e32 v29, v29
	v_add_f32_e32 v24, 1.0, v24
	v_add_f32_e32 v25, 1.0, v25
	v_add_f32_e32 v26, 1.0, v26
	v_add_f32_e32 v27, 1.0, v27
; __device__ __forceinline__ u32x4 pack8(const f32x4 v0, const f32x4 v1) { u32x4 w; w.x = cvt_pk_bf16(v0[0], v0[1]); w.y = cvt_pk_bf16(v0[2], v0[3]); w.z = cvt_pk_bf16(v1[0], v1[1]); w.w = cvt_pk_bf16(v1[2], v1[3]); return w; }
; __device__ __forceinline__ void unpack8(const u32x4 w, f32x4& v0, f32x4& v1) { v0 = (f32x4){bflo(w.x), bfhi(w.x), bflo(w.y), bfhi(w.y)}; v1 = (f32x4){bflo(w.z), bfhi(w.z), bflo(w.w), bfhi(w.w)}; }
; __device__ __forceinline__ f32x4 sig4(const f32x4 v) { return (f32x4){sigmoidf_(v[0]), sigmoidf_(v[1]), sigmoidf_(v[2]), sigmoidf_(v[3])}; }
;     __device__ __forceinline__ void operator()(const AccT& acc, const pg8::Unit& u, int wr, int wc, int fr, int fq) const {
;     ...
;         for (int ai = 0; ai < 2; ++ai) { u32x4 gw[4][2];
; #pragma unroll
;             for (int m = 0; m < 4; ++m)
; #pragma unroll
;                 for (int bj = 0; bj < 2; ++bj) gw[m][bj] = *(const u32x4*)(G + (size_t)(row0 + ai * 128 + m * 16) * 1024 + col0 + bj * 128);
; #pragma unroll
;             for (int m = 0; m < 4; ++m)
; #pragma unroll
;                 for (int bj = 0; bj < 2; ++bj) { f32x4 g0, g1; unpack8(gw[m][bj], g0, g1);
;                     *(u32x4*)(O + (size_t)(row0 + ai * 128 + m * 16) * 1024 + col0 + bj * 128) = pack8(g0 * sig4(acc[ai][bj][m][0] + bv[bj][0]), g1 * sig4(acc[ai][bj][m][1] + bv[bj][1])); } }
	v_mul_f32_e32 v12, 0xbfb8aa3b, v12
	v_mul_f32_e32 v13, 0xbfb8aa3b, v13
	v_pk_add_f32 v[8:9], v[8:9], v[80:81]
	v_pk_add_f32 v[10:11], v[10:11], v[82:83]
	global_store_dwordx4 v[44:45], v[40:43], off sc1
	v_lshlrev_b32_e32 v46, 16, v98
	v_and_b32_e32 v47, 0xffff0000, v98
	v_lshlrev_b32_e32 v40, 16, v96
	v_and_b32_e32 v41, 0xffff0000, v96
	v_lshlrev_b32_e32 v42, 16, v97
	v_and_b32_e32 v43, 0xffff0000, v97
	v_lshlrev_b32_e32 v48, 16, v99
	v_and_b32_e32 v49, 0xffff0000, v99
	v_add_f32_e32 v30, 1.0, v30
	v_add_f32_e32 v31, 1.0, v31
	v_rcp_f32_e32 v24, v24
	v_rcp_f32_e32 v26, v26
	v_rcp_f32_e32 v27, v27
	v_rcp_f32_e32 v25, v25
	v_exp_f32_e32 v12, v12
	v_pk_add_f32 v[14:15], v[14:15], v[86:87]
	v_exp_f32_e32 v13, v13
	v_mul_f32_e32 v8, 0xbfb8aa3b, v8
	v_mul_f32_e32 v9, 0xbfb8aa3b, v9
	v_mul_f32_e32 v10, 0xbfb8aa3b, v10
	v_mul_f32_e32 v11, 0xbfb8aa3b, v11
	v_pk_mul_f32 v[38:39], v[38:39], v[42:43]
	v_pk_mul_f32 v[36:37], v[36:37], v[40:41]
	v_pk_mul_f32 v[40:41], v[34:35], v[48:49]
	v_pk_mul_f32 v[34:35], v[32:33], v[46:47]
	v_cvt_pk_bf16_f32 v32, v36, v37
	v_cvt_pk_bf16_f32 v33, v38, v39
	v_rcp_f32_e32 v30, v30
	v_rcp_f32_e32 v31, v31
	v_mul_f32_e32 v14, 0xbfb8aa3b, v14
	v_mul_f32_e32 v15, 0xbfb8aa3b, v15
	v_exp_f32_e32 v8, v8
	v_exp_f32_e32 v9, v9
	v_exp_f32_e32 v10, v10
	v_exp_f32_e32 v11, v11
	v_cvt_pk_bf16_f32 v34, v34, v35
	v_cvt_pk_bf16_f32 v35, v40, v41
	global_store_dwordx4 v[44:45], v[32:35], off offset:256 sc1
	v_add_f32_e32 v20, 1.0, v20
	v_add_f32_e32 v21, 1.0, v21
	v_lshlrev_b32_e32 v32, 16, v92
	v_and_b32_e32 v33, 0xffff0000, v92
	v_add_f32_e32 v22, 1.0, v22
	v_add_f32_e32 v23, 1.0, v23
	v_add_f32_e32 v16, 1.0, v16
	v_add_f32_e32 v17, 1.0, v17
	v_add_f32_e32 v18, 1.0, v18
	v_add_f32_e32 v19, 1.0, v19
	v_exp_f32_e32 v14, v14
	v_exp_f32_e32 v15, v15
	v_pk_add_f32 v[4:5], v[4:5], v[68:69]
	v_pk_add_f32 v[0:1], v[0:1], v[64:65]
	v_pk_add_f32 v[2:3], v[2:3], v[66:67]
	v_lshlrev_b32_e32 v36, 16, v94
	v_and_b32_e32 v37, 0xffff0000, v94
	v_lshlrev_b32_e32 v38, 16, v95
	v_and_b32_e32 v39, 0xffff0000, v95
	v_pk_mul_f32 v[28:29], v[28:29], v[32:33]
	v_rcp_f32_e32 v20, v20
	v_rcp_f32_e32 v21, v21
	v_rcp_f32_e32 v22, v22
	v_rcp_f32_e32 v23, v23
	v_rcp_f32_e32 v16, v16
	v_rcp_f32_e32 v18, v18
	v_rcp_f32_e32 v19, v19
	v_rcp_f32_e32 v17, v17
	v_mul_f32_e32 v4, 0xbfb8aa3b, v4
	v_pk_add_f32 v[6:7], v[6:7], v[70:71]
	v_mul_f32_e32 v5, 0xbfb8aa3b, v5
	v_mul_f32_e32 v0, 0xbfb8aa3b, v0
	v_mul_f32_e32 v1, 0xbfb8aa3b, v1
	v_mul_f32_e32 v2, 0xbfb8aa3b, v2
	v_mul_f32_e32 v3, 0xbfb8aa3b, v3
	v_lshlrev_b32_e32 v34, 16, v93
	v_and_b32_e32 v35, 0xffff0000, v93
	v_pk_mul_f32 v[32:33], v[26:27], v[38:39]
	v_pk_mul_f32 v[26:27], v[24:25], v[36:37]
	v_cvt_pk_bf16_f32 v24, v28, v29
	v_lshl_add_u64 v[28:29], s[4:5], 0, v[102:103]
	v_add_f32_e32 v12, 1.0, v12
	v_add_f32_e32 v13, 1.0, v13
	v_exp_f32_e32 v4, v4
	v_exp_f32_e32 v5, v5
	v_mul_f32_e32 v6, 0xbfb8aa3b, v6
	v_mul_f32_e32 v7, 0xbfb8aa3b, v7
	v_exp_f32_e32 v0, v0
	v_exp_f32_e32 v1, v1
	v_exp_f32_e32 v2, v2
	v_exp_f32_e32 v3, v3
	v_pk_mul_f32 v[30:31], v[30:31], v[34:35]
	v_lshl_add_u64 v[28:29], v[28:29], 0, v[180:181]
	v_cvt_pk_bf16_f32 v25, v30, v31
	v_cvt_pk_bf16_f32 v26, v26, v27
	v_cvt_pk_bf16_f32 v27, v32, v33
	v_rcp_f32_e32 v12, v12
	v_rcp_f32_e32 v13, v13
	v_add_f32_e32 v8, 1.0, v8
	v_add_f32_e32 v9, 1.0, v9
	v_add_f32_e32 v10, 1.0, v10
	v_add_f32_e32 v11, 1.0, v11
	v_exp_f32_e32 v6, v6
	v_exp_f32_e32 v7, v7
	global_store_dwordx4 v[28:29], v[24:27], off sc1
	v_lshlrev_b32_e32 v30, 16, v90
	v_and_b32_e32 v31, 0xffff0000, v90
	v_lshlrev_b32_e32 v24, 16, v88
	v_and_b32_e32 v25, 0xffff0000, v88
	v_lshlrev_b32_e32 v26, 16, v89
	v_and_b32_e32 v27, 0xffff0000, v89
	v_lshlrev_b32_e32 v32, 16, v91
	v_and_b32_e32 v33, 0xffff0000, v91
	v_add_f32_e32 v14, 1.0, v14
	v_add_f32_e32 v15, 1.0, v15
	v_rcp_f32_e32 v8, v8
	v_rcp_f32_e32 v10, v10
	v_rcp_f32_e32 v11, v11
	v_rcp_f32_e32 v9, v9
	v_pk_mul_f32 v[22:23], v[22:23], v[26:27]
	v_pk_mul_f32 v[20:21], v[20:21], v[24:25]
	v_pk_mul_f32 v[24:25], v[18:19], v[32:33]
	v_pk_mul_f32 v[18:19], v[16:17], v[30:31]
	v_cvt_pk_bf16_f32 v16, v20, v21
	v_cvt_pk_bf16_f32 v17, v22, v23
	v_rcp_f32_e32 v14, v14
	v_rcp_f32_e32 v15, v15
	v_cvt_pk_bf16_f32 v18, v18, v19
	v_cvt_pk_bf16_f32 v19, v24, v25
	global_store_dwordx4 v[28:29], v[16:19], off offset:256 sc1
	v_add_f32_e32 v4, 1.0, v4
	v_add_f32_e32 v5, 1.0, v5
	v_lshlrev_b32_e32 v16, 16, v76
	v_and_b32_e32 v17, 0xffff0000, v76
	v_add_f32_e32 v0, 1.0, v0
	v_add_f32_e32 v1, 1.0, v1
	v_add_f32_e32 v2, 1.0, v2
	v_add_f32_e32 v3, 1.0, v3
	v_lshlrev_b32_e32 v20, 16, v78
	v_and_b32_e32 v21, 0xffff0000, v78
	v_lshlrev_b32_e32 v22, 16, v79
	v_and_b32_e32 v23, 0xffff0000, v79
	v_pk_mul_f32 v[12:13], v[12:13], v[16:17]
	v_rcp_f32_e32 v4, v4
	v_rcp_f32_e32 v5, v5
	v_add_f32_e32 v6, 1.0, v6
	v_add_f32_e32 v7, 1.0, v7
	v_rcp_f32_e32 v0, v0
	v_rcp_f32_e32 v2, v2
	v_rcp_f32_e32 v3, v3
	v_rcp_f32_e32 v1, v1
	v_lshlrev_b32_e32 v18, 16, v77
	v_and_b32_e32 v19, 0xffff0000, v77
	v_pk_mul_f32 v[16:17], v[10:11], v[22:23]
	v_pk_mul_f32 v[10:11], v[8:9], v[20:21]
	v_cvt_pk_bf16_f32 v8, v12, v13
	v_lshl_add_u64 v[12:13], s[4:5], 0, v[100:101]
	v_rcp_f32_e32 v6, v6
	v_rcp_f32_e32 v7, v7
	v_pk_mul_f32 v[14:15], v[14:15], v[18:19]
	v_lshl_add_u64 v[12:13], v[12:13], 0, v[180:181]
	v_cvt_pk_bf16_f32 v9, v14, v15
	v_cvt_pk_bf16_f32 v10, v10, v11
	v_cvt_pk_bf16_f32 v11, v16, v17
	global_store_dwordx4 v[12:13], v[8:11], off sc1
	v_lshlrev_b32_e32 v14, 16, v74
	v_and_b32_e32 v15, 0xffff0000, v74
	v_lshlrev_b32_e32 v8, 16, v72
	v_and_b32_e32 v9, 0xffff0000, v72
	v_lshlrev_b32_e32 v16, 16, v75
	v_and_b32_e32 v17, 0xffff0000, v75
	v_lshlrev_b32_e32 v10, 16, v73
	v_and_b32_e32 v11, 0xffff0000, v73
	v_pk_mul_f32 v[4:5], v[4:5], v[8:9]
	v_pk_mul_f32 v[8:9], v[2:3], v[16:17]
	v_pk_mul_f32 v[2:3], v[0:1], v[14:15]
	v_pk_mul_f32 v[6:7], v[6:7], v[10:11]
	v_cvt_pk_bf16_f32 v0, v4, v5
	s_nop 0
	v_cvt_pk_bf16_f32 v1, v6, v7
	v_cvt_pk_bf16_f32 v2, v2, v3
	v_cvt_pk_bf16_f32 v3, v8, v9
	global_store_dwordx4 v[12:13], v[0:3], off offset:256 sc1
	s_cbranch_vccz .LBB0_732
	s_waitcnt vmcnt(0)
	s_cmpk_gt_u32 s33, 0xff
	s_cbranch_scc1 .LBB0_743
	s_barrier

; __device__ __forceinline__ unsigned cvt_pk_bf16(float lo, float hi) { unsigned r; asm volatile("v_cvt_pk_bf16_f32 %0, %1, %2" : "=v"(r) : "v"(lo), "v"(hi)); return r; }
; __device__ __forceinline__ void convert_dynamic(const Params& P, unsigned char* shm, unsigned* ctr, int t0, int t1) {
;     ...
;         for (int h = 0; h < 4; ++h) { d[h] = tile_desc(P, t + h < t1 ? t + h : t);
; #pragma unroll
;             for (int i = 0; i < 4; ++i) v[h][i] = *(const f32x4*)(d[h].src + (size_t)(r0 + 32 * i) * d[h].ld + c4 * 4); }
; #pragma unroll
;         for (int h = 0; h < 4; ++h) {
;             if (t + h < t1) {
; #pragma unroll
;                 for (int i = 0; i < 4; ++i) { float* tp = tile + (r0 + 32 * i) * 65 + c4 * 4; tp[0] = v[h][i][0]; tp[1] = v[h][i][1]; tp[2] = v[h][i][2]; tp[3] = v[h][i][3]; }
;                 __syncthreads();
;                 { const int n = tid >> 3, kc = tid & 7; float x[16];
; #pragma unroll
;                   for (int jj = 0; jj < 8; ++jj) { x[jj] = tile[(kc * 8 + jj) * 65 + n]; x[8 + jj] = tile[(64 + kc * 8 + jj) * 65 + n]; }
;                   u32x4 w0, w1; w0.x = cvt_pk_bf16(x[0], x[1]); w0.y = cvt_pk_bf16(x[2], x[3]); w0.z = cvt_pk_bf16(x[4], x[5]); w0.w = cvt_pk_bf16(x[6], x[7]);
;                   w1.x = cvt_pk_bf16(x[8], x[9]); w1.y = cvt_pk_bf16(x[10], x[11]); w1.z = cvt_pk_bf16(x[12], x[13]); w1.w = cvt_pk_bf16(x[14], x[15]);
;                   bf16_t* dp = d[h].dst + (size_t)n * d[h].ldd + kc * 8; *(u32x4*)dp = w0; *(u32x4*)(dp + 64) = w1; }
;                 __syncthreads();
.LBB0_842:
	s_or_b64 exec, exec, s[34:35]
	v_lshl_add_u64 v[58:59], v[48:49], 0, v[66:67]
	v_mul_u32_u24_e32 v48, v56, v193
	v_lshlrev_b32_e32 v66, 2, v48
	v_mul_hi_u32_u24_e32 v51, v56, v65
	v_mul_u32_u24_e32 v50, v56, v65
	v_mul_hi_u32_u24_e32 v61, v56, v69
	v_mul_u32_u24_e32 v60, v56, v69
	v_mul_hi_u32_u24_e32 v57, v56, v86
	v_mul_u32_u24_e32 v56, v56, v86
	v_lshl_add_u64 v[48:49], v[58:59], 0, v[66:67]
	v_lshl_add_u64 v[50:51], v[50:51], 2, v[58:59]
	v_lshl_add_u64 v[60:61], v[60:61], 2, v[58:59]
	v_lshl_add_u64 v[56:57], v[56:57], 2, v[58:59]
	global_load_dwordx4 v[52:55], v[48:49], off
	s_nop 0
	global_load_dwordx4 v[48:51], v[50:51], off
	s_nop 0
	global_load_dwordx4 v[60:63], v[60:61], off
	s_nop 0
	global_load_dwordx4 v[56:59], v[56:57], off
	s_waitcnt vmcnt(15)
	ds_write2_b32 v90, v4, v5 offset1:1
	ds_write2_b32 v90, v6, v7 offset0:2 offset1:3
	v_add_u32_e32 v4, 0x2080, v90
	s_waitcnt vmcnt(14)
	ds_write2_b32 v4, v0, v1 offset1:1
	v_add_u32_e32 v0, 0x2088, v90
	ds_write2_b32 v0, v2, v3 offset1:1
	v_add_u32_e32 v1, 0x4100, v90
	v_add_u32_e32 v2, 0x4108, v90
	v_add_u32_e32 v5, 0x6180, v90
	v_add_u32_e32 v6, 0x6188, v90
	v_add_u32_e32 v3, 0x400, v87
	s_waitcnt vmcnt(13)
	ds_write2_b32 v1, v12, v13 offset1:1
	ds_write2_b32 v2, v14, v15 offset1:1
	s_waitcnt vmcnt(12)
	ds_write2_b32 v5, v8, v9 offset1:1
	ds_write2_b32 v6, v10, v11 offset1:1
	s_waitcnt lgkmcnt(0)
	s_barrier
	ds_read2_b32 v[12:13], v87 offset1:65
	ds_read2_b32 v[14:15], v87 offset0:130 offset1:195
	ds_read2_b32 v[92:93], v3 offset0:4 offset1:69
	ds_read2_b32 v[94:95], v3 offset0:134 offset1:199
	v_mul_u32_u24_e32 v11, v72, v192
	v_lshlrev_b32_e32 v66, 1, v11
	v_add_u32_e32 v7, 0x4000, v88
	v_add_u32_e32 v8, 0x4200, v88
	v_add_u32_e32 v9, 0x4400, v88
	v_add_u32_e32 v10, 0x4600, v88
	v_lshl_add_u64 v[70:71], v[70:71], 0, v[66:67]
	v_lshlrev_b32_e32 v66, 1, v68
	ds_read2_b32 v[96:97], v7 offset0:64 offset1:129
	ds_read2_b32 v[98:99], v8 offset0:66 offset1:131
	ds_read2_b32 v[100:101], v9 offset0:68 offset1:133
	ds_read2_b32 v[102:103], v10 offset0:70 offset1:135
	s_waitcnt lgkmcnt(7)
	v_cvt_pk_bf16_f32 v12, v12, v13
	s_waitcnt lgkmcnt(6)
	v_cvt_pk_bf16_f32 v13, v14, v15
	s_waitcnt lgkmcnt(5)
	v_cvt_pk_bf16_f32 v14, v92, v93
	s_waitcnt lgkmcnt(4)
	v_cvt_pk_bf16_f32 v15, v94, v95
	v_lshl_add_u64 v[70:71], v[70:71], 0, v[66:67]
	s_waitcnt lgkmcnt(3)
	v_cvt_pk_bf16_f32 v92, v96, v97
	s_waitcnt lgkmcnt(2)
	v_cvt_pk_bf16_f32 v93, v98, v99
	s_waitcnt lgkmcnt(1)
	v_cvt_pk_bf16_f32 v94, v100, v101
	s_waitcnt lgkmcnt(0)
	v_cvt_pk_bf16_f32 v95, v102, v103
	global_store_dwordx4 v[70:71], v[12:15], off sc1
	global_store_dwordx4 v[70:71], v[92:95], off offset:128 sc1
	s_barrier
	s_and_saveexec_b64 s[0:1], vcc
	s_cbranch_execnz .LBB0_845
	s_or_b64 exec, exec, s[0:1]
	s_and_saveexec_b64 s[0:1], s[2:3]
	s_cbranch_execnz .LBB0_846

; __device__ __forceinline__ unsigned cvt_pk_bf16(float lo, float hi) { unsigned r; asm volatile("v_cvt_pk_bf16_f32 %0, %1, %2" : "=v"(r) : "v"(lo), "v"(hi)); return r; }
; __device__ __forceinline__ void convert_dynamic(const Params& P, unsigned char* shm, unsigned* ctr, int t0, int t1) {
;     ...
;         for (int h = 0; h < 4; ++h) {
;             if (t + h < t1) {
; #pragma unroll
;                 for (int i = 0; i < 4; ++i) { float* tp = tile + (r0 + 32 * i) * 65 + c4 * 4; tp[0] = v[h][i][0]; tp[1] = v[h][i][1]; tp[2] = v[h][i][2]; tp[3] = v[h][i][3]; }
;                 __syncthreads();
;                 { const int n = tid >> 3, kc = tid & 7; float x[16];
; #pragma unroll
;                   for (int jj = 0; jj < 8; ++jj) { x[jj] = tile[(kc * 8 + jj) * 65 + n]; x[8 + jj] = tile[(64 + kc * 8 + jj) * 65 + n]; }
;                   u32x4 w0, w1; w0.x = cvt_pk_bf16(x[0], x[1]); w0.y = cvt_pk_bf16(x[2], x[3]); w0.z = cvt_pk_bf16(x[4], x[5]); w0.w = cvt_pk_bf16(x[6], x[7]);
;                   w1.x = cvt_pk_bf16(x[8], x[9]); w1.y = cvt_pk_bf16(x[10], x[11]); w1.z = cvt_pk_bf16(x[12], x[13]); w1.w = cvt_pk_bf16(x[14], x[15]);
;                   bf16_t* dp = d[h].dst + (size_t)n * d[h].ldd + kc * 8; *(u32x4*)dp = w0; *(u32x4*)(dp + 64) = w1; }
;                 __syncthreads();
.LBB0_845:
	s_waitcnt vmcnt(13)
	ds_write2_b32 v90, v20, v21 offset1:1
	ds_write2_b32 v90, v22, v23 offset0:2 offset1:3
	s_waitcnt vmcnt(12)
	ds_write2_b32 v4, v16, v17 offset1:1
	ds_write2_b32 v0, v18, v19 offset1:1
	s_waitcnt vmcnt(11)
	ds_write2_b32 v1, v28, v29 offset1:1
	ds_write2_b32 v2, v30, v31 offset1:1
	s_waitcnt vmcnt(10)
	ds_write2_b32 v5, v24, v25 offset1:1
	ds_write2_b32 v6, v26, v27 offset1:1
	s_waitcnt lgkmcnt(0)
	s_barrier
	ds_read2_b32 v[12:13], v87 offset1:65
	ds_read2_b32 v[14:15], v87 offset0:130 offset1:195
	ds_read2_b32 v[16:17], v3 offset0:4 offset1:69
	ds_read2_b32 v[18:19], v3 offset0:134 offset1:199
	ds_read2_b32 v[20:21], v7 offset0:64 offset1:129
	ds_read2_b32 v[22:23], v8 offset0:66 offset1:131
	ds_read2_b32 v[24:25], v9 offset0:68 offset1:133
	ds_read2_b32 v[26:27], v10 offset0:70 offset1:135
	v_mul_u32_u24_e32 v11, v76, v192
	s_waitcnt lgkmcnt(7)
	v_cvt_pk_bf16_f32 v12, v12, v13
	s_waitcnt lgkmcnt(6)
	v_cvt_pk_bf16_f32 v13, v14, v15
	s_waitcnt lgkmcnt(5)
	v_cvt_pk_bf16_f32 v14, v16, v17
	s_waitcnt lgkmcnt(4)
	v_cvt_pk_bf16_f32 v15, v18, v19
	s_waitcnt lgkmcnt(3)
	v_cvt_pk_bf16_f32 v16, v20, v21
	v_lshlrev_b32_e32 v20, 1, v11
	v_mov_b32_e32 v21, v67
	v_lshl_add_u64 v[20:21], v[74:75], 0, v[20:21]
	v_lshl_add_u64 v[20:21], v[20:21], 0, v[66:67]
	s_waitcnt lgkmcnt(2)
	v_cvt_pk_bf16_f32 v17, v22, v23
	s_waitcnt lgkmcnt(1)
	v_cvt_pk_bf16_f32 v18, v24, v25
	s_waitcnt lgkmcnt(0)
	v_cvt_pk_bf16_f32 v19, v26, v27
	global_store_dwordx4 v[20:21], v[12:15], off sc1
	global_store_dwordx4 v[20:21], v[16:19], off offset:128 sc1
	s_barrier
	s_or_b64 exec, exec, s[0:1]
	s_and_saveexec_b64 s[0:1], s[2:3]
	s_cbranch_execz .LBB0_844
.LBB0_846:
	s_waitcnt vmcnt(9)
	ds_write2_b32 v90, v36, v37 offset1:1
	ds_write2_b32 v90, v38, v39 offset0:2 offset1:3
	s_waitcnt vmcnt(8)
	ds_write2_b32 v4, v32, v33 offset1:1
	ds_write2_b32 v0, v34, v35 offset1:1
	s_waitcnt vmcnt(7)
	ds_write2_b32 v1, v44, v45 offset1:1
	ds_write2_b32 v2, v46, v47 offset1:1
	s_waitcnt vmcnt(6)
	ds_write2_b32 v5, v40, v41 offset1:1
	ds_write2_b32 v6, v42, v43 offset1:1
	s_waitcnt lgkmcnt(0)
	s_barrier
	ds_read2_b32 v[12:13], v87 offset1:65
	ds_read2_b32 v[14:15], v87 offset0:130 offset1:195
	ds_read2_b32 v[16:17], v3 offset0:4 offset1:69
	ds_read2_b32 v[18:19], v3 offset0:134 offset1:199
	ds_read2_b32 v[20:21], v7 offset0:64 offset1:129
	ds_read2_b32 v[22:23], v8 offset0:66 offset1:131
	ds_read2_b32 v[24:25], v9 offset0:68 offset1:133
	ds_read2_b32 v[26:27], v10 offset0:70 offset1:135
	v_mul_u32_u24_e32 v11, v80, v192
	s_waitcnt lgkmcnt(7)
	v_cvt_pk_bf16_f32 v12, v12, v13
	s_waitcnt lgkmcnt(6)
	v_cvt_pk_bf16_f32 v13, v14, v15
	s_waitcnt lgkmcnt(5)
	v_cvt_pk_bf16_f32 v14, v16, v17
	s_waitcnt lgkmcnt(4)
	v_cvt_pk_bf16_f32 v15, v18, v19
	s_waitcnt lgkmcnt(3)
	v_cvt_pk_bf16_f32 v16, v20, v21
	v_lshlrev_b32_e32 v20, 1, v11
	v_mov_b32_e32 v21, v67
	v_lshl_add_u64 v[20:21], v[78:79], 0, v[20:21]
	v_lshl_add_u64 v[20:21], v[20:21], 0, v[66:67]
	s_waitcnt lgkmcnt(2)
	v_cvt_pk_bf16_f32 v17, v22, v23
	s_waitcnt lgkmcnt(1)
	v_cvt_pk_bf16_f32 v18, v24, v25
	s_waitcnt lgkmcnt(0)
	v_cvt_pk_bf16_f32 v19, v26, v27
	global_store_dwordx4 v[20:21], v[12:15], off sc1
	global_store_dwordx4 v[20:21], v[16:19], off offset:128 sc1
	s_barrier
	s_or_b64 exec, exec, s[0:1]
	s_and_saveexec_b64 s[0:1], s[4:5]
	s_xor_b64 s[0:1], exec, s[0:1]
	s_cbranch_execz .LBB0_745
.LBB0_847:
	s_waitcnt vmcnt(5)
	ds_write2_b32 v90, v52, v53 offset1:1
	ds_write2_b32 v90, v54, v55 offset0:2 offset1:3
	s_waitcnt vmcnt(4)
	ds_write2_b32 v4, v48, v49 offset1:1
	ds_write2_b32 v0, v50, v51 offset1:1
	s_waitcnt vmcnt(3)
	ds_write2_b32 v1, v60, v61 offset1:1
	ds_write2_b32 v2, v62, v63 offset1:1
	s_waitcnt vmcnt(2)
	ds_write2_b32 v5, v56, v57 offset1:1
	ds_write2_b32 v6, v58, v59 offset1:1
	s_waitcnt lgkmcnt(0)
	s_barrier
	ds_read2_b32 v[0:1], v87 offset1:65
	ds_read2_b32 v[4:5], v87 offset0:130 offset1:195
	ds_read2_b32 v[12:13], v3 offset0:4 offset1:69
	ds_read2_b32 v[14:15], v3 offset0:134 offset1:199
	ds_read2_b32 v[6:7], v7 offset0:64 offset1:129
	ds_read2_b32 v[16:17], v8 offset0:66 offset1:131
	ds_read2_b32 v[8:9], v9 offset0:68 offset1:133
	ds_read2_b32 v[10:11], v10 offset0:70 offset1:135
	s_waitcnt lgkmcnt(7)
	v_cvt_pk_bf16_f32 v0, v0, v1
	s_waitcnt lgkmcnt(6)
	v_cvt_pk_bf16_f32 v1, v4, v5
	s_waitcnt lgkmcnt(5)
	v_cvt_pk_bf16_f32 v2, v12, v13
	s_waitcnt lgkmcnt(4)
	v_cvt_pk_bf16_f32 v3, v14, v15
	s_waitcnt lgkmcnt(3)
	v_cvt_pk_bf16_f32 v4, v6, v7
	s_waitcnt lgkmcnt(2)
	v_cvt_pk_bf16_f32 v5, v16, v17
	s_waitcnt lgkmcnt(1)
	v_cvt_pk_bf16_f32 v6, v8, v9
	v_mul_u32_u24_e32 v8, v84, v192
	v_lshlrev_b32_e32 v8, 1, v8
	v_mov_b32_e32 v9, v67
	v_lshl_add_u64 v[8:9], v[82:83], 0, v[8:9]
	v_lshl_add_u64 v[8:9], v[8:9], 0, v[66:67]
	s_waitcnt lgkmcnt(0)
	v_cvt_pk_bf16_f32 v7, v10, v11
	global_store_dwordx4 v[8:9], v[0:3], off sc1
	global_store_dwordx4 v[8:9], v[4:7], off offset:128 sc1
	s_barrier
	s_branch .LBB0_745
